# v53 + P7 prologue: first chunk's U loads issued right after the weight loads (latency under the coefficient precompute), prologue vmcnt waits +4
# speedup vs baseline: 1.0007x; 1.0007x over previous
; template <int DIR>
; __device__ __forceinline__ void s5_local_dir(const bf16_t* UZ, unsigned char* ws, int gw, int NGW, int lane) {
;     float* E = (float*)(ws + WS_E);
;     const int pair = gw & 127, g = pair & 63, fr = lane & 15, fq = lane >> 4;
;     const bf16_t* Bb = (const bf16_t*)(ws + WS_BB) + (size_t)pair * 128 * 16;
;     bf16x4 Bre[4][4], Bim[4][4]; float a1r[4], a1i[4], a64r[4], a64i[4], wr_[4], wi_[4];
; #pragma unroll
;     for (int t = 0; t < 4; ++t) {
;         const int p = 16 * t + fr;
;         const bf16x4 b_re = *(const bf16x4*)(Bb + (2 * p) * 16 + 4 * fq), b_im = *(const bf16x4*)(Bb + (2 * p + 1) * 16 + 4 * fq);
;         const f32x4 ap = ((const f32x4*)(ws + WS_APOW))[pair * 64 + p];
;         const float ar = ap.x, ai = ap.y;
;         float r2 = ar, i2 = ai; cmul(r2, i2, ar, ai);
;         float r4 = r2, i4 = i2; cmul(r4, i4, r2, i2);
;         float r8 = r4, i8 = i4; cmul(r8, i8, r4, i4);
;         float r12 = r8, i12 = i8; cmul(r12, i12, r4, i4);
;         float r16 = r8, i16 = i8; cmul(r16, i16, r8, i8);
;         float r32 = r16, i32 = i16; cmul(r32, i32, r16, i16);
;         float r48 = r32, i48 = i32; cmul(r48, i48, r16, i16);
;         a1r[t] = ar; a1i[t] = ai; a64r[t] = ap.z; a64i[t] = ap.w;
;         const int e = DIR ? fq : 3 - fq;
;         wr_[t] = e == 0 ? 1.f : e == 1 ? r4 : e == 2 ? r8 : r12; wi_[t] = e == 0 ? 0.f : e == 1 ? i4 : e == 2 ? i8 : i12;
; #pragma unroll
;         for (int m = 0; m < 4; ++m) {
;             const int em = DIR ? m : 3 - m;
;             const float pr = em == 0 ? 1.f : em == 1 ? r16 : em == 2 ? r32 : r48, pi = em == 0 ? 0.f : em == 1 ? i16 : em == 2 ? i32 : i48;
;             Bre[m][t] = cscale_bf(b_re, b_im, pr, pi, false); Bim[m][t] = cscale_bf(b_re, b_im, pr, pi, true);
;         }
;     }
;     const int qd = gw >> 7, b = qd >> 2, q = qd & 3;
;     if (qd >= 16) return;
;     const int c0 = 17 * q, c1 = q < 3 ? c0 + 17 : 67;
;     float Rr[4] = {0.f, 0.f, 0.f, 0.f}, Ri[4] = {0.f, 0.f, 0.f, 0.f};
;     float* ebase = E + ((size_t)((b * 2 + DIR) * 64 + g) * NCHUNK) * 128;
;     bf16x4 Un[4];
;     load_uf(Un, UZ, chunk_rowbase(b, DIR, c0), g, lane);
; __device__ __forceinline__ void s5_local_phase(LAS unsigned char* lds, const bf16_t* UZ, unsigned char* ws) {
;     const int lane = threadIdx.x & 63, wave = __builtin_amdgcn_readfirstlane(threadIdx.x >> 6);
.LBB0_644:
	s_cmp_lt_i32 s68, 8
	s_cselect_b64 s[0:1], -1, 0
	s_and_b64 s[0:1], s[0:1], s[2:3]
	s_andn2_b64 vcc, exec, s[0:1]
	s_cbranch_vccnz .LBB0_690
	v_readfirstlane_b32 s2, v192
	s_lshr_b32 s40, s2, 6
	s_lshl_b32 s2, s12, 3
	s_add_i32 s40, s40, s2
	s_and_b32 s2, s40, 64
	s_add_u32 s41, s30, 0x100000
	s_addc_u32 s42, s31, 0
	s_add_u32 s4, s30, 0x80000
	s_addc_u32 s5, s31, 0
	v_and_b32_e32 v127, 15, v192
	v_bfe_u32 v128, v192, 4, 2
	v_and_b32_e32 v126, 63, v192
	s_cmp_eq_u32 s2, 0
	v_lshlrev_b32_e32 v129, 2, v128
	v_lshlrev_b32_e32 v130, 5, v127
	s_cbranch_scc1 .LBB0_662
	s_ashr_i32 s2, s40, 7
	s_cmp_lt_i32 s2, 16
	s_mov_b64 s[22:23], 0
	s_cbranch_scc0 .LBB0_663
	s_and_b32 s43, s2, 3
	s_mul_i32 s38, s43, 17
	s_ashr_i32 s36, s40, 9
	s_and_b32 s44, s40, 63
	s_add_i32 s37, s38, 17
	s_cmp_lg_u32 s43, 3
	s_cselect_b64 s[24:25], -1, 0
	s_and_b64 s[2:3], s[24:25], exec
	s_cselect_b32 s46, s37, 0x43
	s_lshl_b32 s45, s36, 7
	v_cmp_gt_u32_e64 s[8:9], 16, v126
	v_mov_b32_e32 v115, 0
	v_mov_b32_e32 v240, 0
	v_mov_b32_e32 v241, 0
	s_cmp_ge_u32 s38, s46
	v_mov_b32_e32 v114, 0
	v_mov_b32_e32 v112, 0
	v_mov_b32_e32 v110, 0
	v_mov_b32_e32 v113, 0
	v_mov_b32_e32 v111, 0
	v_mov_b32_e32 v109, 0
	v_mov_b32_e32 v108, 0
	s_cbranch_scc1 .LBB0_684
	s_and_b32 s37, s40, 0x7f
	s_lshl_b32 s2, s37, 12
	s_add_u32 s2, s41, s2
	s_addc_u32 s3, s42, 0
	s_lshl_b32 s37, s37, 6
	s_waitcnt vmcnt(0)
	v_or_b32_e32 v0, s37, v127
	v_lshlrev_b32_e32 v0, 4, v0
	global_load_dwordx4 v[0:3], v0, s[4:5]
	v_lshlrev_b32_e32 v16, 1, v130
	v_mov_b32_e32 v17, 0
	v_lshl_add_u64 v[4:5], s[2:3], 0, v[16:17]
	v_lshlrev_b32_e32 v16, 1, v129
	v_lshl_add_u64 v[4:5], v[4:5], 0, v[16:17]
	global_load_dwordx2 v[22:23], v[4:5], off
	global_load_dwordx2 v[26:27], v[4:5], off offset:32
	v_or_b32_e32 v10, 16, v127
	v_or_b32_e32 v11, 32, v127
	v_or_b32_e32 v12, 48, v126
	v_lshlrev_b32_e32 v4, 6, v10
	v_mov_b32_e32 v5, v17
	v_lshlrev_b32_e32 v6, 6, v11
	v_mov_b32_e32 v7, v17
	v_lshlrev_b32_e32 v8, 6, v12
	v_mov_b32_e32 v9, v17
	v_lshl_add_u64 v[4:5], s[2:3], 0, v[4:5]
	v_lshrrev_b32_e32 v13, 1, v192
	v_or_b32_e32 v10, s37, v10
	v_lshl_add_u64 v[6:7], s[2:3], 0, v[6:7]
	v_or_b32_e32 v11, s37, v11
	v_lshl_add_u64 v[8:9], s[2:3], 0, v[8:9]
	v_or_b32_e32 v12, s37, v12
	v_lshl_add_u64 v[18:19], v[4:5], 0, v[16:17]
	v_lshlrev_b32_e32 v28, 4, v10
	v_lshl_add_u64 v[20:21], v[6:7], 0, v[16:17]
	v_lshlrev_b32_e32 v29, 4, v11
	v_lshl_add_u64 v[24:25], v[8:9], 0, v[16:17]
	v_lshlrev_b32_e32 v30, 4, v12
	v_and_b32_e32 v16, 24, v13
	global_load_dwordx2 v[50:51], v[18:19], off
	global_load_dwordx2 v[48:49], v[18:19], off offset:32
	global_load_dwordx4 v[4:7], v28, s[4:5]
	global_load_dwordx2 v[72:73], v[20:21], off
	global_load_dwordx2 v[70:71], v[20:21], off offset:32
	global_load_dwordx4 v[8:11], v29, s[4:5]
	global_load_dwordx2 v[94:95], v[24:25], off
	global_load_dwordx2 v[92:93], v[24:25], off offset:32
	global_load_dwordx4 v[12:15], v30, s[4:5]
	s_lshl_b32 s98, s36, 8
	s_addk_i32 s98, 0x40c0
	s_lshl_b32 s99, s36, 12
	s_addk_i32 s99, 0x10c0
	s_cmp_eq_u32 s43, 0
	s_cselect_b32 s98, s98, s99
	s_mul_i32 s99, s43, 0xfffffbc0
	s_lshl_b32 s100, s44, 5
	s_add_u32 s100, s18, s100
	s_addc_u32 s101, s19, 0
	v_or_b32_e32 v160, s99, v127
	v_add_u32_e32 v160, s98, v160
	v_ashrrev_i32_e32 v161, 31, v160
	v_lshlrev_b64 v[162:163], 12, v[160:161]
	v_lshrrev_b32_e32 v164, 1, v192
	v_and_b32_e32 v164, 24, v164
	v_mov_b32_e32 v165, 0
	v_lshl_add_u64 v[162:163], s[100:101], 0, v[162:163]
	v_lshl_add_u64 v[162:163], v[162:163], 0, v[164:165]
	s_mov_b32 s98, 0x10000
	s_mov_b32 s99, 0
	v_lshl_add_u64 v[164:165], v[162:163], 0, s[98:99]
	v_lshl_add_u64 v[166:167], v[164:165], 0, s[98:99]
	v_lshl_add_u64 v[168:169], v[166:167], 0, s[98:99]
	global_load_dwordx2 v[152:153], v[162:163], off
	global_load_dwordx2 v[154:155], v[164:165], off
	global_load_dwordx2 v[156:157], v[166:167], off
	global_load_dwordx2 v[158:159], v[168:169], off
	s_lshl_b32 s39, s44, 5
	s_add_u32 s2, s18, s39
	s_addc_u32 s3, s19, 0
	v_cmp_eq_u32_e32 vcc, 2, v128
	v_lshl_add_u64 v[18:19], s[2:3], 0, v[16:17]
	v_cmp_eq_u32_e64 s[2:3], 1, v128
	s_mov_b32 s37, 0x5040100
	s_lshl_b32 s47, s36, 8
	s_lshl_b32 s48, s36, 12
	s_addk_i32 s47, 0x40c0
	s_addk_i32 s48, 0x10c0
	s_cmp_eq_u32 s43, 0
	s_waitcnt vmcnt(15)
	v_pk_mul_f32 v[24:25], v[0:1], v[0:1] op_sel:[1,1] op_sel_hi:[1,0]
	s_nop 0
	v_pk_fma_f32 v[28:29], v[0:1], v[0:1], v[24:25] op_sel_hi:[1,0,1] neg_lo:[0,0,1] neg_hi:[0,0,1]
	v_pk_fma_f32 v[24:25], v[0:1], v[0:1], v[24:25] op_sel_hi:[1,0,1]
	v_mov_b32_e32 v30, v28
	v_pk_mov_b32 v[32:33], v[24:25], v[28:29] op_sel:[1,0]
	v_mov_b32_e32 v31, v25
	v_pk_mul_f32 v[24:25], v[24:25], v[32:33] op_sel:[1,0]
	v_mov_b32_e32 v20, v0
	v_pk_fma_f32 v[32:33], v[28:29], v[30:31], v[24:25] op_sel_hi:[0,1,1] neg_lo:[0,0,1] neg_hi:[0,0,1]
	v_pk_fma_f32 v[24:25], v[28:29], v[30:31], v[24:25] op_sel_hi:[0,1,1]
	v_pk_mov_b32 v[30:31], v[24:25], v[32:33] op_sel:[1,0]
	v_mov_b32_e32 v28, v32
	v_mov_b32_e32 v29, v25
	v_pk_mul_f32 v[30:31], v[24:25], v[30:31] op_sel:[1,0]
	v_mov_b32_e32 v21, v0
	v_pk_fma_f32 v[34:35], v[32:33], v[28:29], v[30:31] op_sel_hi:[0,1,1] neg_lo:[0,0,1] neg_hi:[0,0,1]
	v_pk_fma_f32 v[30:31], v[32:33], v[28:29], v[30:31] op_sel_hi:[0,1,1]
	v_pk_mov_b32 v[38:39], v[30:31], v[34:35] op_sel:[1,0]
	v_mov_b32_e32 v36, v34
	v_mov_b32_e32 v37, v31
	v_pk_mul_f32 v[38:39], v[30:31], v[38:39] op_sel:[1,0]
	v_mul_f32_e32 v0, v25, v34
	v_pk_mul_f32 v[28:29], v[28:29], v[36:37]
	v_pk_fma_f32 v[44:45], v[34:35], v[36:37], v[38:39] op_sel_hi:[0,1,1] neg_lo:[0,0,1] neg_hi:[0,0,1]
	v_pk_fma_f32 v[36:37], v[34:35], v[36:37], v[38:39] op_sel_hi:[0,1,1]
	v_fmac_f32_e32 v0, v32, v31
	v_pk_mov_b32 v[38:39], v[36:37], v[44:45] op_sel:[1,0]
	v_sub_f32_e32 v16, v28, v29
	v_mov_b32_e32 v28, v44
	v_mov_b32_e32 v29, v37
	v_cndmask_b32_e32 v0, v0, v31, vcc
	v_pk_mul_f32 v[30:31], v[36:37], v[38:39] op_sel:[1,0]
	v_cndmask_b32_e64 v0, v0, v25, s[2:3]
	v_pk_fma_f32 v[46:47], v[44:45], v[28:29], v[30:31] op_sel_hi:[0,1,1] neg_lo:[0,0,1] neg_hi:[0,0,1]
	v_pk_fma_f32 v[52:53], v[44:45], v[28:29], v[30:31] op_sel_hi:[0,1,1]
	s_waitcnt vmcnt(13)
; template <int DIR>
; __device__ __forceinline__ void s5_local_dir(const bf16_t* UZ, unsigned char* ws, int gw, int NGW, int lane) {
;     ...
;     for (int t = 0; t < 4; ++t) {
;         const int p = 16 * t + fr;
;         const bf16x4 b_re = *(const bf16x4*)(Bb + (2 * p) * 16 + 4 * fq), b_im = *(const bf16x4*)(Bb + (2 * p + 1) * 16 + 4 * fq);
;         const f32x4 ap = ((const f32x4*)(ws + WS_APOW))[pair * 64 + p];
;         const float ar = ap.x, ai = ap.y;
;         float r2 = ar, i2 = ai; cmul(r2, i2, ar, ai);
;         float r4 = r2, i4 = i2; cmul(r4, i4, r2, i2);
;         float r8 = r4, i8 = i4; cmul(r8, i8, r4, i4);
;         float r12 = r8, i12 = i8; cmul(r12, i12, r4, i4);
;         float r16 = r8, i16 = i8; cmul(r16, i16, r8, i8);
;         float r32 = r16, i32 = i16; cmul(r32, i32, r16, i16);
;         float r48 = r32, i48 = i32; cmul(r48, i48, r16, i16);
;         a1r[t] = ar; a1i[t] = ai; a64r[t] = ap.z; a64i[t] = ap.w;
;         const int e = DIR ? fq : 3 - fq;
;         wr_[t] = e == 0 ? 1.f : e == 1 ? r4 : e == 2 ? r8 : r12; wi_[t] = e == 0 ? 0.f : e == 1 ? i4 : e == 2 ? i8 : i12;
; #pragma unroll
;         for (int m = 0; m < 4; ++m) {
;             const int em = DIR ? m : 3 - m;
;             const float pr = em == 0 ? 1.f : em == 1 ? r16 : em == 2 ? r32 : r48, pi = em == 0 ? 0.f : em == 1 ? i16 : em == 2 ? i32 : i48;
;             Bre[m][t] = cscale_bf(b_re, b_im, pr, pi, false); Bim[m][t] = cscale_bf(b_re, b_im, pr, pi, true);
;         }
	v_and_b32_e32 v43, 0xffff0000, v26
	v_lshlrev_b32_e32 v42, 16, v26
	v_cndmask_b32_e32 v16, v16, v34, vcc
	v_cndmask_b32_e64 v25, v0, 0, s[8:9]
	v_mov_b32_e32 v30, v46
	v_mov_b32_e32 v31, v53
	v_mul_f32_e32 v0, v37, v53
	v_and_b32_e32 v61, 0xffff0000, v27
	v_lshlrev_b32_e32 v60, 16, v27
	v_and_b32_e32 v41, 0xffff0000, v22
	v_lshlrev_b32_e32 v40, 16, v22
	v_cndmask_b32_e64 v16, v16, v32, s[2:3]
	v_pk_fma_f32 v[54:55], v[28:29], v[30:31], v[0:1] op_sel_hi:[1,1,0] neg_lo:[0,0,1] neg_hi:[0,0,1]
	v_and_b32_e32 v59, 0xffff0000, v23
	v_lshlrev_b32_e32 v58, 16, v23
	v_xor_b32_e32 v27, 0x80000000, v61
	v_xor_b32_e32 v26, 0x80000000, v60
	v_xor_b32_e32 v29, 0x80000000, v43
	v_xor_b32_e32 v28, 0x80000000, v42
	v_cndmask_b32_e64 v22, v16, 1.0, s[8:9]
	v_mul_f32_e32 v16, v44, v53
	v_pk_fma_f32 v[26:27], v[26:27], 0, v[58:59] op_sel_hi:[1,0,1]
	v_pk_fma_f32 v[28:29], v[28:29], 0, v[40:41] op_sel_hi:[1,0,1]
	v_pk_fma_f32 v[56:57], v[38:39], v[30:31], v[16:17] op_sel_hi:[1,1,0]
	v_cvt_pk_bf16_f32 v0, v28, s0
	v_cvt_pk_bf16_f32 v16, v29, s0
	v_cvt_pk_bf16_f32 v23, v26, s0
	v_cvt_pk_bf16_f32 v24, v27, s0
	v_pk_fma_f32 v[28:29], v[58:59], 0, v[60:61] op_sel_hi:[1,0,1]
	v_pk_fma_f32 v[30:31], v[40:41], 0, v[42:43] op_sel_hi:[1,0,1]
	v_pk_mul_f32 v[32:33], v[36:37], v[60:61] op_sel:[1,0]
	v_perm_b32 v27, v24, v23, s37
	v_perm_b32 v26, v16, v0, s37
	v_cvt_pk_bf16_f32 v0, v30, s0
	v_cvt_pk_bf16_f32 v16, v31, s0
	v_cvt_pk_bf16_f32 v23, v28, s0
	v_cvt_pk_bf16_f32 v24, v29, s0
	v_pk_mul_f32 v[30:31], v[36:37], v[42:43] op_sel:[1,0]
	v_pk_fma_f32 v[32:33], v[44:45], v[58:59], v[32:33] op_sel_hi:[0,1,1] neg_lo:[0,0,1] neg_hi:[0,0,1]
	v_pk_mul_f32 v[34:35], v[36:37], v[58:59] op_sel:[1,0]
	v_perm_b32 v29, v24, v23, s37
	v_pk_fma_f32 v[30:31], v[44:45], v[40:41], v[30:31] op_sel_hi:[0,1,1] neg_lo:[0,0,1] neg_hi:[0,0,1]
	v_cvt_pk_bf16_f32 v23, v32, s0
	v_cvt_pk_bf16_f32 v24, v33, s0
	v_pk_mul_f32 v[32:33], v[36:37], v[40:41] op_sel:[1,0]
	v_pk_fma_f32 v[34:35], v[44:45], v[60:61], v[34:35] op_sel_hi:[0,1,1]
	v_pk_mul_f32 v[36:37], v[52:53], v[60:61] op_sel:[1,0]
	v_perm_b32 v28, v16, v0, s37
	v_cvt_pk_bf16_f32 v0, v30, s0
	v_cvt_pk_bf16_f32 v16, v31, s0
	v_perm_b32 v31, v24, v23, s37
	v_pk_fma_f32 v[32:33], v[44:45], v[42:43], v[32:33] op_sel_hi:[0,1,1]
	v_cvt_pk_bf16_f32 v23, v34, s0
	v_cvt_pk_bf16_f32 v24, v35, s0
	v_pk_mul_f32 v[34:35], v[52:53], v[42:43] op_sel:[1,0]
	v_pk_fma_f32 v[36:37], v[46:47], v[58:59], v[36:37] op_sel_hi:[0,1,1] neg_lo:[0,0,1] neg_hi:[0,0,1]
	v_pk_mul_f32 v[38:39], v[52:53], v[58:59] op_sel:[1,0]
	v_perm_b32 v30, v16, v0, s37
	v_cvt_pk_bf16_f32 v0, v32, s0
	v_cvt_pk_bf16_f32 v16, v33, s0
	v_perm_b32 v33, v24, v23, s37
	v_pk_fma_f32 v[34:35], v[46:47], v[40:41], v[34:35] op_sel_hi:[0,1,1] neg_lo:[0,0,1] neg_hi:[0,0,1]
	v_cvt_pk_bf16_f32 v23, v36, s0
	v_cvt_pk_bf16_f32 v24, v37, s0
	v_pk_mul_f32 v[36:37], v[52:53], v[40:41] op_sel:[1,0]
	v_pk_fma_f32 v[38:39], v[46:47], v[60:61], v[38:39] op_sel_hi:[0,1,1]
	v_pk_mul_f32 v[44:45], v[56:57], v[60:61] op_sel_hi:[0,1]
	v_perm_b32 v32, v16, v0, s37
	v_cvt_pk_bf16_f32 v0, v34, s0
	v_cvt_pk_bf16_f32 v16, v35, s0
	v_perm_b32 v35, v24, v23, s37
	v_pk_fma_f32 v[36:37], v[46:47], v[42:43], v[36:37] op_sel_hi:[0,1,1]
	v_cvt_pk_bf16_f32 v23, v38, s0
	v_cvt_pk_bf16_f32 v24, v39, s0
	v_pk_fma_f32 v[44:45], v[54:55], v[58:59], v[44:45] op_sel_hi:[0,1,1] neg_lo:[0,0,1] neg_hi:[0,0,1]
	v_perm_b32 v34, v16, v0, s37
	v_cvt_pk_bf16_f32 v16, v37, s0
	v_perm_b32 v37, v24, v23, s37
	v_pk_mul_f32 v[38:39], v[56:57], v[42:43] op_sel_hi:[0,1]
	v_cvt_pk_bf16_f32 v23, v44, s0
	v_cvt_pk_bf16_f32 v24, v45, s0
	v_pk_mul_f32 v[44:45], v[56:57], v[58:59] op_sel_hi:[0,1]
	v_cvt_pk_bf16_f32 v0, v36, s0
	v_pk_fma_f32 v[38:39], v[54:55], v[40:41], v[38:39] op_sel_hi:[0,1,1] neg_lo:[0,0,1] neg_hi:[0,0,1]
	v_pk_fma_f32 v[44:45], v[54:55], v[60:61], v[44:45] op_sel_hi:[0,1,1]
	v_perm_b32 v36, v16, v0, s37
	v_cvt_pk_bf16_f32 v16, v39, s0
	v_perm_b32 v39, v24, v23, s37
	v_cvt_pk_bf16_f32 v23, v44, s0
	v_cvt_pk_bf16_f32 v24, v45, s0
	s_waitcnt vmcnt(10)
	v_pk_mul_f32 v[44:45], v[4:5], v[4:5] op_sel:[1,1] op_sel_hi:[1,0]
	v_pk_mul_f32 v[40:41], v[56:57], v[40:41] op_sel_hi:[0,1]
	v_pk_fma_f32 v[46:47], v[4:5], v[4:5], v[44:45] op_sel_hi:[1,0,1] neg_lo:[0,0,1] neg_hi:[0,0,1]
	v_pk_fma_f32 v[44:45], v[4:5], v[4:5], v[44:45] op_sel_hi:[1,0,1]
	v_pk_fma_f32 v[40:41], v[54:55], v[42:43], v[40:41] op_sel_hi:[0,1,1]
	v_pk_mov_b32 v[54:55], v[44:45], v[46:47] op_sel:[1,0]
	v_mov_b32_e32 v52, v46
	v_mov_b32_e32 v53, v45
	v_pk_mul_f32 v[44:45], v[44:45], v[54:55] op_sel:[1,0]
	v_cvt_pk_bf16_f32 v0, v38, s0
	v_pk_fma_f32 v[54:55], v[46:47], v[52:53], v[44:45] op_sel_hi:[0,1,1] neg_lo:[0,0,1] neg_hi:[0,0,1]
	v_pk_fma_f32 v[44:45], v[46:47], v[52:53], v[44:45] op_sel_hi:[0,1,1]
	v_pk_mov_b32 v[52:53], v[44:45], v[54:55] op_sel:[1,0]
	v_mov_b32_e32 v46, v54
	v_mov_b32_e32 v47, v45
	v_pk_mul_f32 v[52:53], v[44:45], v[52:53] op_sel:[1,0]
	v_perm_b32 v38, v16, v0, s37
	v_pk_fma_f32 v[56:57], v[54:55], v[46:47], v[52:53] op_sel_hi:[0,1,1] neg_lo:[0,0,1] neg_hi:[0,0,1]
	v_pk_fma_f32 v[52:53], v[54:55], v[46:47], v[52:53] op_sel_hi:[0,1,1]
	v_pk_mov_b32 v[60:61], v[52:53], v[56:57] op_sel:[1,0]
	v_mov_b32_e32 v58, v56
	v_mov_b32_e32 v59, v53
	v_pk_mul_f32 v[60:61], v[52:53], v[60:61] op_sel:[1,0]
	v_cvt_pk_bf16_f32 v0, v40, s0
	v_pk_fma_f32 v[62:63], v[56:57], v[58:59], v[60:61] op_sel_hi:[0,1,1] neg_lo:[0,0,1] neg_hi:[0,0,1]
	v_pk_fma_f32 v[60:61], v[56:57], v[58:59], v[60:61] op_sel_hi:[0,1,1]
	v_pk_mov_b32 v[66:67], v[60:61], v[62:63] op_sel:[1,0]
	v_mov_b32_e32 v64, v62
	v_mov_b32_e32 v65, v61
	v_pk_mul_f32 v[68:69], v[60:61], v[66:67] op_sel:[1,0]
; template <int DIR>
; __device__ __forceinline__ void s5_local_dir(const bf16_t* UZ, unsigned char* ws, int gw, int NGW, int lane) {
;     ...
;     for (int t = 0; t < 4; ++t) {
;         const int p = 16 * t + fr;
;         const bf16x4 b_re = *(const bf16x4*)(Bb + (2 * p) * 16 + 4 * fq), b_im = *(const bf16x4*)(Bb + (2 * p + 1) * 16 + 4 * fq);
;         const f32x4 ap = ((const f32x4*)(ws + WS_APOW))[pair * 64 + p];
;         const float ar = ap.x, ai = ap.y;
;         float r2 = ar, i2 = ai; cmul(r2, i2, ar, ai);
;         float r4 = r2, i4 = i2; cmul(r4, i4, r2, i2);
;         float r8 = r4, i8 = i4; cmul(r8, i8, r4, i4);
;         float r12 = r8, i12 = i8; cmul(r12, i12, r4, i4);
;         float r16 = r8, i16 = i8; cmul(r16, i16, r8, i8);
;         float r32 = r16, i32 = i16; cmul(r32, i32, r16, i16);
;         float r48 = r32, i48 = i32; cmul(r48, i48, r16, i16);
;         a1r[t] = ar; a1i[t] = ai; a64r[t] = ap.z; a64i[t] = ap.w;
;         const int e = DIR ? fq : 3 - fq;
;         wr_[t] = e == 0 ? 1.f : e == 1 ? r4 : e == 2 ? r8 : r12; wi_[t] = e == 0 ? 0.f : e == 1 ? i4 : e == 2 ? i8 : i12;
; #pragma unroll
;         for (int m = 0; m < 4; ++m) {
;             const int em = DIR ? m : 3 - m;
;             const float pr = em == 0 ? 1.f : em == 1 ? r16 : em == 2 ? r32 : r48, pi = em == 0 ? 0.f : em == 1 ? i16 : em == 2 ? i32 : i48;
;             Bre[m][t] = cscale_bf(b_re, b_im, pr, pi, false); Bim[m][t] = cscale_bf(b_re, b_im, pr, pi, true);
;         }
	v_cvt_pk_bf16_f32 v16, v41, s0
	v_pk_fma_f32 v[74:75], v[62:63], v[64:65], v[68:69] op_sel_hi:[0,1,1] neg_lo:[0,0,1] neg_hi:[0,0,1]
	v_pk_fma_f32 v[68:69], v[62:63], v[64:65], v[68:69] op_sel_hi:[0,1,1]
	v_perm_b32 v40, v16, v0, s37
	v_mov_b32_e32 v76, v74
	v_mov_b32_e32 v77, v69
	v_mul_f32_e32 v0, v61, v69
	v_pk_fma_f32 v[64:65], v[64:65], v[76:77], v[0:1] op_sel_hi:[1,1,0] neg_lo:[0,0,1] neg_hi:[0,0,1]
	v_mul_f32_e32 v0, v62, v69
	v_pk_fma_f32 v[66:67], v[66:67], v[76:77], v[0:1] op_sel_hi:[1,1,0]
	v_mul_f32_e32 v0, v45, v56
	v_pk_mul_f32 v[46:47], v[46:47], v[58:59]
	v_mov_b32_e32 v42, v4
	v_mov_b32_e32 v43, v4
	v_fmac_f32_e32 v0, v54, v53
	v_sub_f32_e32 v4, v46, v47
	v_and_b32_e32 v79, 0xffff0000, v48
	v_lshlrev_b32_e32 v78, 16, v48
	v_and_b32_e32 v83, 0xffff0000, v49
	v_lshlrev_b32_e32 v82, 16, v49
	v_cndmask_b32_e32 v4, v4, v56, vcc
	v_cndmask_b32_e32 v0, v0, v53, vcc
	v_and_b32_e32 v77, 0xffff0000, v50
	v_lshlrev_b32_e32 v76, 16, v50
	v_and_b32_e32 v81, 0xffff0000, v51
	v_lshlrev_b32_e32 v80, 16, v51
	v_xor_b32_e32 v49, 0x80000000, v83
	v_xor_b32_e32 v48, 0x80000000, v82
	v_xor_b32_e32 v51, 0x80000000, v79
	v_xor_b32_e32 v50, 0x80000000, v78
	v_cndmask_b32_e64 v4, v4, v54, s[2:3]
	v_cndmask_b32_e64 v0, v0, v45, s[2:3]
	v_pk_fma_f32 v[48:49], v[48:49], 0, v[80:81] op_sel_hi:[1,0,1]
	v_pk_fma_f32 v[50:51], v[50:51], 0, v[76:77] op_sel_hi:[1,0,1]
	v_perm_b32 v41, v24, v23, s37
	v_cndmask_b32_e64 v44, v4, 1.0, s[8:9]
	v_cndmask_b32_e64 v47, v0, 0, s[8:9]
	v_cvt_pk_bf16_f32 v0, v50, s0
	v_cvt_pk_bf16_f32 v4, v51, s0
	v_cvt_pk_bf16_f32 v16, v48, s0
	v_cvt_pk_bf16_f32 v23, v49, s0
	v_pk_fma_f32 v[50:51], v[80:81], 0, v[82:83] op_sel_hi:[1,0,1]
	v_pk_fma_f32 v[52:53], v[76:77], 0, v[78:79] op_sel_hi:[1,0,1]
	v_pk_mul_f32 v[54:55], v[60:61], v[82:83] op_sel:[1,0]
	v_perm_b32 v49, v23, v16, s37
	v_perm_b32 v48, v4, v0, s37
	v_cvt_pk_bf16_f32 v0, v52, s0
	v_cvt_pk_bf16_f32 v4, v53, s0
	v_cvt_pk_bf16_f32 v16, v50, s0
	v_cvt_pk_bf16_f32 v23, v51, s0
	v_pk_mul_f32 v[52:53], v[60:61], v[78:79] op_sel:[1,0]
	v_pk_fma_f32 v[54:55], v[62:63], v[80:81], v[54:55] op_sel_hi:[0,1,1] neg_lo:[0,0,1] neg_hi:[0,0,1]
	v_pk_mul_f32 v[56:57], v[60:61], v[80:81] op_sel:[1,0]
	v_perm_b32 v51, v23, v16, s37
	v_pk_fma_f32 v[52:53], v[62:63], v[76:77], v[52:53] op_sel_hi:[0,1,1] neg_lo:[0,0,1] neg_hi:[0,0,1]
	v_cvt_pk_bf16_f32 v16, v54, s0
	v_cvt_pk_bf16_f32 v23, v55, s0
	v_pk_mul_f32 v[54:55], v[60:61], v[76:77] op_sel:[1,0]
	v_pk_fma_f32 v[56:57], v[62:63], v[82:83], v[56:57] op_sel_hi:[0,1,1]
	v_pk_mul_f32 v[58:59], v[68:69], v[82:83] op_sel:[1,0]
	v_perm_b32 v50, v4, v0, s37
	v_cvt_pk_bf16_f32 v0, v52, s0
	v_cvt_pk_bf16_f32 v4, v53, s0
	v_perm_b32 v53, v23, v16, s37
	v_pk_fma_f32 v[54:55], v[62:63], v[78:79], v[54:55] op_sel_hi:[0,1,1]
	v_cvt_pk_bf16_f32 v16, v56, s0
	v_cvt_pk_bf16_f32 v23, v57, s0
	v_pk_mul_f32 v[56:57], v[68:69], v[78:79] op_sel:[1,0]
	v_pk_fma_f32 v[58:59], v[74:75], v[80:81], v[58:59] op_sel_hi:[0,1,1] neg_lo:[0,0,1] neg_hi:[0,0,1]
	v_pk_mul_f32 v[60:61], v[68:69], v[80:81] op_sel:[1,0]
	v_perm_b32 v52, v4, v0, s37
	v_cvt_pk_bf16_f32 v0, v54, s0
	v_cvt_pk_bf16_f32 v4, v55, s0
	v_perm_b32 v55, v23, v16, s37
	v_pk_fma_f32 v[56:57], v[74:75], v[76:77], v[56:57] op_sel_hi:[0,1,1] neg_lo:[0,0,1] neg_hi:[0,0,1]
	v_cvt_pk_bf16_f32 v16, v58, s0
	v_cvt_pk_bf16_f32 v23, v59, s0
	v_pk_mul_f32 v[58:59], v[68:69], v[76:77] op_sel:[1,0]
	v_pk_fma_f32 v[60:61], v[74:75], v[82:83], v[60:61] op_sel_hi:[0,1,1]
	v_pk_mul_f32 v[62:63], v[66:67], v[82:83] op_sel_hi:[0,1]
	v_perm_b32 v54, v4, v0, s37
	v_cvt_pk_bf16_f32 v0, v56, s0
	v_cvt_pk_bf16_f32 v4, v57, s0
	v_perm_b32 v57, v23, v16, s37
	v_pk_fma_f32 v[58:59], v[74:75], v[78:79], v[58:59] op_sel_hi:[0,1,1]
	v_cvt_pk_bf16_f32 v16, v60, s0
	v_cvt_pk_bf16_f32 v23, v61, s0
	v_pk_fma_f32 v[62:63], v[64:65], v[80:81], v[62:63] op_sel_hi:[0,1,1] neg_lo:[0,0,1] neg_hi:[0,0,1]
	v_perm_b32 v56, v4, v0, s37
	v_cvt_pk_bf16_f32 v4, v59, s0
	v_perm_b32 v59, v23, v16, s37
	v_pk_mul_f32 v[60:61], v[66:67], v[78:79] op_sel_hi:[0,1]
	v_cvt_pk_bf16_f32 v16, v62, s0
	v_cvt_pk_bf16_f32 v23, v63, s0
	v_pk_mul_f32 v[62:63], v[66:67], v[76:77] op_sel_hi:[0,1]
	v_pk_mul_f32 v[66:67], v[66:67], v[80:81] op_sel_hi:[0,1]
	v_cvt_pk_bf16_f32 v0, v58, s0
	v_pk_fma_f32 v[60:61], v[64:65], v[76:77], v[60:61] op_sel_hi:[0,1,1] neg_lo:[0,0,1] neg_hi:[0,0,1]
	v_pk_fma_f32 v[66:67], v[64:65], v[82:83], v[66:67] op_sel_hi:[0,1,1]
	v_perm_b32 v58, v4, v0, s37
	v_cvt_pk_bf16_f32 v4, v61, s0
	v_perm_b32 v61, v23, v16, s37
	v_cvt_pk_bf16_f32 v16, v66, s0
	v_cvt_pk_bf16_f32 v23, v67, s0
	s_waitcnt vmcnt(7)
; template <int DIR>
; __device__ __forceinline__ void s5_local_dir(const bf16_t* UZ, unsigned char* ws, int gw, int NGW, int lane) {
;     ...
;     for (int t = 0; t < 4; ++t) {
;         const int p = 16 * t + fr;
;         const bf16x4 b_re = *(const bf16x4*)(Bb + (2 * p) * 16 + 4 * fq), b_im = *(const bf16x4*)(Bb + (2 * p + 1) * 16 + 4 * fq);
;         const f32x4 ap = ((const f32x4*)(ws + WS_APOW))[pair * 64 + p];
;         const float ar = ap.x, ai = ap.y;
;         float r2 = ar, i2 = ai; cmul(r2, i2, ar, ai);
;         float r4 = r2, i4 = i2; cmul(r4, i4, r2, i2);
;         float r8 = r4, i8 = i4; cmul(r8, i8, r4, i4);
;         float r12 = r8, i12 = i8; cmul(r12, i12, r4, i4);
;         float r16 = r8, i16 = i8; cmul(r16, i16, r8, i8);
;         float r32 = r16, i32 = i16; cmul(r32, i32, r16, i16);
;         float r48 = r32, i48 = i32; cmul(r48, i48, r16, i16);
;         a1r[t] = ar; a1i[t] = ai; a64r[t] = ap.z; a64i[t] = ap.w;
;         const int e = DIR ? fq : 3 - fq;
;         wr_[t] = e == 0 ? 1.f : e == 1 ? r4 : e == 2 ? r8 : r12; wi_[t] = e == 0 ? 0.f : e == 1 ? i4 : e == 2 ? i8 : i12;
; #pragma unroll
;         for (int m = 0; m < 4; ++m) {
;             const int em = DIR ? m : 3 - m;
;             const float pr = em == 0 ? 1.f : em == 1 ? r16 : em == 2 ? r32 : r48, pi = em == 0 ? 0.f : em == 1 ? i16 : em == 2 ? i32 : i48;
;             Bre[m][t] = cscale_bf(b_re, b_im, pr, pi, false); Bim[m][t] = cscale_bf(b_re, b_im, pr, pi, true);
;         }
	v_pk_mul_f32 v[66:67], v[8:9], v[8:9] op_sel:[1,1] op_sel_hi:[1,0]
	v_pk_fma_f32 v[62:63], v[64:65], v[78:79], v[62:63] op_sel_hi:[0,1,1]
	v_pk_fma_f32 v[68:69], v[8:9], v[8:9], v[66:67] op_sel_hi:[1,0,1] neg_lo:[0,0,1] neg_hi:[0,0,1]
	v_pk_fma_f32 v[66:67], v[8:9], v[8:9], v[66:67] op_sel_hi:[1,0,1]
	v_mov_b32_e32 v74, v68
	v_pk_mov_b32 v[76:77], v[66:67], v[68:69] op_sel:[1,0]
	v_mov_b32_e32 v75, v67
	v_pk_mul_f32 v[66:67], v[66:67], v[76:77] op_sel:[1,0]
	v_cvt_pk_bf16_f32 v0, v60, s0
	v_pk_fma_f32 v[76:77], v[68:69], v[74:75], v[66:67] op_sel_hi:[0,1,1] neg_lo:[0,0,1] neg_hi:[0,0,1]
	v_pk_fma_f32 v[66:67], v[68:69], v[74:75], v[66:67] op_sel_hi:[0,1,1]
	v_pk_mov_b32 v[74:75], v[66:67], v[76:77] op_sel:[1,0]
	v_mov_b32_e32 v68, v76
	v_mov_b32_e32 v69, v67
	v_pk_mul_f32 v[74:75], v[66:67], v[74:75] op_sel:[1,0]
	v_perm_b32 v60, v4, v0, s37
	v_pk_fma_f32 v[78:79], v[76:77], v[68:69], v[74:75] op_sel_hi:[0,1,1] neg_lo:[0,0,1] neg_hi:[0,0,1]
	v_pk_fma_f32 v[74:75], v[76:77], v[68:69], v[74:75] op_sel_hi:[0,1,1]
	v_pk_mov_b32 v[82:83], v[74:75], v[78:79] op_sel:[1,0]
	v_mov_b32_e32 v80, v78
	v_mov_b32_e32 v81, v75
	v_pk_mul_f32 v[82:83], v[74:75], v[82:83] op_sel:[1,0]
	v_cvt_pk_bf16_f32 v0, v62, s0
	v_pk_fma_f32 v[84:85], v[78:79], v[80:81], v[82:83] op_sel_hi:[0,1,1] neg_lo:[0,0,1] neg_hi:[0,0,1]
	v_pk_fma_f32 v[82:83], v[78:79], v[80:81], v[82:83] op_sel_hi:[0,1,1]
	v_pk_mov_b32 v[88:89], v[82:83], v[84:85] op_sel:[1,0]
	v_mov_b32_e32 v86, v84
	v_mov_b32_e32 v87, v83
	v_pk_mul_f32 v[90:91], v[82:83], v[88:89] op_sel:[1,0]
	v_cvt_pk_bf16_f32 v4, v63, s0
	v_pk_fma_f32 v[96:97], v[84:85], v[86:87], v[90:91] op_sel_hi:[0,1,1] neg_lo:[0,0,1] neg_hi:[0,0,1]
	v_pk_fma_f32 v[90:91], v[84:85], v[86:87], v[90:91] op_sel_hi:[0,1,1]
	v_perm_b32 v62, v4, v0, s37
	v_mov_b32_e32 v98, v96
	v_mov_b32_e32 v99, v91
	v_mul_f32_e32 v0, v83, v91
	v_pk_fma_f32 v[86:87], v[86:87], v[98:99], v[0:1] op_sel_hi:[1,1,0] neg_lo:[0,0,1] neg_hi:[0,0,1]
	v_mul_f32_e32 v0, v84, v91
	v_pk_fma_f32 v[88:89], v[88:89], v[98:99], v[0:1] op_sel_hi:[1,1,0]
	v_mul_f32_e32 v0, v67, v78
	v_pk_mul_f32 v[68:69], v[68:69], v[80:81]
	v_fmac_f32_e32 v0, v76, v75
	v_sub_f32_e32 v4, v68, v69
	v_and_b32_e32 v101, 0xffff0000, v70
	v_lshlrev_b32_e32 v100, 16, v70
	v_and_b32_e32 v105, 0xffff0000, v71
	v_lshlrev_b32_e32 v104, 16, v71
	v_cndmask_b32_e32 v4, v4, v78, vcc
	v_cndmask_b32_e32 v0, v0, v75, vcc
	v_and_b32_e32 v99, 0xffff0000, v72
	v_lshlrev_b32_e32 v98, 16, v72
	v_and_b32_e32 v103, 0xffff0000, v73
	v_lshlrev_b32_e32 v102, 16, v73
	v_xor_b32_e32 v71, 0x80000000, v105
	v_xor_b32_e32 v70, 0x80000000, v104
	v_xor_b32_e32 v73, 0x80000000, v101
	v_xor_b32_e32 v72, 0x80000000, v100
	v_cndmask_b32_e64 v4, v4, v76, s[2:3]
	v_cndmask_b32_e64 v0, v0, v67, s[2:3]
	v_pk_fma_f32 v[70:71], v[70:71], 0, v[102:103] op_sel_hi:[1,0,1]
	v_pk_fma_f32 v[72:73], v[72:73], 0, v[98:99] op_sel_hi:[1,0,1]
	v_perm_b32 v63, v23, v16, s37
	v_mov_b32_e32 v64, v8
	v_mov_b32_e32 v65, v8
	v_cndmask_b32_e64 v66, v4, 1.0, s[8:9]
	v_cndmask_b32_e64 v69, v0, 0, s[8:9]
	v_cvt_pk_bf16_f32 v0, v72, s0
	v_cvt_pk_bf16_f32 v4, v73, s0
	v_cvt_pk_bf16_f32 v8, v70, s0
	v_cvt_pk_bf16_f32 v16, v71, s0
	v_pk_fma_f32 v[72:73], v[102:103], 0, v[104:105] op_sel_hi:[1,0,1]
	v_pk_fma_f32 v[74:75], v[98:99], 0, v[100:101] op_sel_hi:[1,0,1]
	v_pk_mul_f32 v[76:77], v[82:83], v[104:105] op_sel:[1,0]
	v_perm_b32 v71, v16, v8, s37
	v_perm_b32 v70, v4, v0, s37
	v_cvt_pk_bf16_f32 v0, v74, s0
	v_cvt_pk_bf16_f32 v4, v75, s0
	v_cvt_pk_bf16_f32 v8, v72, s0
	v_cvt_pk_bf16_f32 v16, v73, s0
	v_pk_mul_f32 v[74:75], v[82:83], v[100:101] op_sel:[1,0]
	v_pk_fma_f32 v[76:77], v[84:85], v[102:103], v[76:77] op_sel_hi:[0,1,1] neg_lo:[0,0,1] neg_hi:[0,0,1]
	v_pk_mul_f32 v[78:79], v[82:83], v[102:103] op_sel:[1,0]
	v_perm_b32 v73, v16, v8, s37
	v_pk_fma_f32 v[74:75], v[84:85], v[98:99], v[74:75] op_sel_hi:[0,1,1] neg_lo:[0,0,1] neg_hi:[0,0,1]
	v_cvt_pk_bf16_f32 v8, v76, s0
	v_cvt_pk_bf16_f32 v16, v77, s0
	v_pk_mul_f32 v[76:77], v[82:83], v[98:99] op_sel:[1,0]
	v_pk_fma_f32 v[78:79], v[84:85], v[104:105], v[78:79] op_sel_hi:[0,1,1]
	v_pk_mul_f32 v[80:81], v[90:91], v[104:105] op_sel:[1,0]
	v_perm_b32 v72, v4, v0, s37
	v_cvt_pk_bf16_f32 v0, v74, s0
	v_cvt_pk_bf16_f32 v4, v75, s0
	v_perm_b32 v75, v16, v8, s37
	v_pk_fma_f32 v[76:77], v[84:85], v[100:101], v[76:77] op_sel_hi:[0,1,1]
	v_cvt_pk_bf16_f32 v8, v78, s0
	v_cvt_pk_bf16_f32 v16, v79, s0
	v_pk_mul_f32 v[78:79], v[90:91], v[100:101] op_sel:[1,0]
	v_pk_fma_f32 v[80:81], v[96:97], v[102:103], v[80:81] op_sel_hi:[0,1,1] neg_lo:[0,0,1] neg_hi:[0,0,1]
	v_pk_mul_f32 v[82:83], v[90:91], v[102:103] op_sel:[1,0]
	v_perm_b32 v74, v4, v0, s37
	v_cvt_pk_bf16_f32 v0, v76, s0
	v_cvt_pk_bf16_f32 v4, v77, s0
	v_perm_b32 v77, v16, v8, s37
	v_pk_fma_f32 v[78:79], v[96:97], v[98:99], v[78:79] op_sel_hi:[0,1,1] neg_lo:[0,0,1] neg_hi:[0,0,1]
	v_cvt_pk_bf16_f32 v8, v80, s0
	v_cvt_pk_bf16_f32 v16, v81, s0
	v_pk_mul_f32 v[80:81], v[90:91], v[98:99] op_sel:[1,0]
	v_pk_fma_f32 v[82:83], v[96:97], v[104:105], v[82:83] op_sel_hi:[0,1,1]
	v_pk_mul_f32 v[84:85], v[88:89], v[104:105] op_sel_hi:[0,1]
	v_perm_b32 v76, v4, v0, s37
	v_cvt_pk_bf16_f32 v0, v78, s0
	v_cvt_pk_bf16_f32 v4, v79, s0
	v_perm_b32 v79, v16, v8, s37
	v_pk_fma_f32 v[80:81], v[96:97], v[100:101], v[80:81] op_sel_hi:[0,1,1]
	v_cvt_pk_bf16_f32 v8, v82, s0
	v_cvt_pk_bf16_f32 v16, v83, s0
	v_pk_fma_f32 v[84:85], v[86:87], v[102:103], v[84:85] op_sel_hi:[0,1,1] neg_lo:[0,0,1] neg_hi:[0,0,1]
	v_perm_b32 v78, v4, v0, s37
	v_cvt_pk_bf16_f32 v4, v81, s0
	v_perm_b32 v81, v16, v8, s37
	v_pk_mul_f32 v[82:83], v[88:89], v[100:101] op_sel_hi:[0,1]
	v_cvt_pk_bf16_f32 v8, v84, s0
	v_cvt_pk_bf16_f32 v16, v85, s0
	v_pk_mul_f32 v[84:85], v[88:89], v[98:99] op_sel_hi:[0,1]
	v_pk_mul_f32 v[88:89], v[88:89], v[102:103] op_sel_hi:[0,1]
	v_cvt_pk_bf16_f32 v0, v80, s0
	v_pk_fma_f32 v[82:83], v[86:87], v[98:99], v[82:83] op_sel_hi:[0,1,1] neg_lo:[0,0,1] neg_hi:[0,0,1]
	v_pk_fma_f32 v[88:89], v[86:87], v[104:105], v[88:89] op_sel_hi:[0,1,1]
	v_perm_b32 v80, v4, v0, s37
	v_cvt_pk_bf16_f32 v4, v83, s0
	v_perm_b32 v83, v16, v8, s37
	v_cvt_pk_bf16_f32 v8, v88, s0
	v_cvt_pk_bf16_f32 v16, v89, s0
	s_waitcnt vmcnt(4)
; __device__ __forceinline__ void load_uf(bf16x4 (&Uf)[4], const bf16_t* UZ, int rowbase, int g, int lane) {
; #pragma unroll
;     for (int m = 0; m < 4; ++m) Uf[m] = *(const bf16x4*)(UZ + (size_t)(rowbase + 16 * m + (lane & 15)) * NUZ + 16 * g + 4 * (lane >> 4));
; }
; template <int DIR>
; __device__ __forceinline__ void s5_local_dir(const bf16_t* UZ, unsigned char* ws, int gw, int NGW, int lane) {
;     ...
;     for (int t = 0; t < 4; ++t) {
;         const int p = 16 * t + fr;
;         const bf16x4 b_re = *(const bf16x4*)(Bb + (2 * p) * 16 + 4 * fq), b_im = *(const bf16x4*)(Bb + (2 * p + 1) * 16 + 4 * fq);
;         const f32x4 ap = ((const f32x4*)(ws + WS_APOW))[pair * 64 + p];
;         const float ar = ap.x, ai = ap.y;
;         float r2 = ar, i2 = ai; cmul(r2, i2, ar, ai);
;         float r4 = r2, i4 = i2; cmul(r4, i4, r2, i2);
;         float r8 = r4, i8 = i4; cmul(r8, i8, r4, i4);
;         float r12 = r8, i12 = i8; cmul(r12, i12, r4, i4);
;         float r16 = r8, i16 = i8; cmul(r16, i16, r8, i8);
;         float r32 = r16, i32 = i16; cmul(r32, i32, r16, i16);
;         float r48 = r32, i48 = i32; cmul(r48, i48, r16, i16);
;         a1r[t] = ar; a1i[t] = ai; a64r[t] = ap.z; a64i[t] = ap.w;
;         const int e = DIR ? fq : 3 - fq;
;         wr_[t] = e == 0 ? 1.f : e == 1 ? r4 : e == 2 ? r8 : r12; wi_[t] = e == 0 ? 0.f : e == 1 ? i4 : e == 2 ? i8 : i12;
; #pragma unroll
;         for (int m = 0; m < 4; ++m) {
;             const int em = DIR ? m : 3 - m;
;             const float pr = em == 0 ? 1.f : em == 1 ? r16 : em == 2 ? r32 : r48, pi = em == 0 ? 0.f : em == 1 ? i16 : em == 2 ? i32 : i48;
;             Bre[m][t] = cscale_bf(b_re, b_im, pr, pi, false); Bim[m][t] = cscale_bf(b_re, b_im, pr, pi, true);
;         }
	v_pk_mul_f32 v[88:89], v[12:13], v[12:13] op_sel:[1,1] op_sel_hi:[1,0]
	v_pk_fma_f32 v[84:85], v[86:87], v[100:101], v[84:85] op_sel_hi:[0,1,1]
	v_pk_fma_f32 v[90:91], v[12:13], v[12:13], v[88:89] op_sel_hi:[1,0,1] neg_lo:[0,0,1] neg_hi:[0,0,1]
	v_pk_fma_f32 v[88:89], v[12:13], v[12:13], v[88:89] op_sel_hi:[1,0,1]
	v_mov_b32_e32 v96, v90
	v_pk_mov_b32 v[98:99], v[88:89], v[90:91] op_sel:[1,0]
	v_mov_b32_e32 v97, v89
	v_pk_mul_f32 v[88:89], v[88:89], v[98:99] op_sel:[1,0]
	v_cvt_pk_bf16_f32 v0, v82, s0
	v_pk_fma_f32 v[98:99], v[90:91], v[96:97], v[88:89] op_sel_hi:[0,1,1] neg_lo:[0,0,1] neg_hi:[0,0,1]
	v_pk_fma_f32 v[88:89], v[90:91], v[96:97], v[88:89] op_sel_hi:[0,1,1]
	v_pk_mov_b32 v[96:97], v[88:89], v[98:99] op_sel:[1,0]
	v_mov_b32_e32 v90, v98
	v_mov_b32_e32 v91, v89
	v_pk_mul_f32 v[96:97], v[88:89], v[96:97] op_sel:[1,0]
	v_perm_b32 v82, v4, v0, s37
	v_pk_fma_f32 v[100:101], v[98:99], v[90:91], v[96:97] op_sel_hi:[0,1,1] neg_lo:[0,0,1] neg_hi:[0,0,1]
	v_pk_fma_f32 v[96:97], v[98:99], v[90:91], v[96:97] op_sel_hi:[0,1,1]
	v_pk_mov_b32 v[104:105], v[96:97], v[100:101] op_sel:[1,0]
	v_mov_b32_e32 v102, v100
	v_mov_b32_e32 v103, v97
	v_pk_mul_f32 v[104:105], v[96:97], v[104:105] op_sel:[1,0]
	v_cvt_pk_bf16_f32 v0, v84, s0
	v_pk_fma_f32 v[106:107], v[100:101], v[102:103], v[104:105] op_sel_hi:[0,1,1] neg_lo:[0,0,1] neg_hi:[0,0,1]
	v_pk_fma_f32 v[104:105], v[100:101], v[102:103], v[104:105] op_sel_hi:[0,1,1]
	v_pk_mov_b32 v[110:111], v[104:105], v[106:107] op_sel:[1,0]
	v_mov_b32_e32 v108, v106
	v_mov_b32_e32 v109, v105
	v_pk_mul_f32 v[112:113], v[104:105], v[110:111] op_sel:[1,0]
	v_cvt_pk_bf16_f32 v4, v85, s0
	v_pk_fma_f32 v[116:117], v[106:107], v[108:109], v[112:113] op_sel_hi:[0,1,1] neg_lo:[0,0,1] neg_hi:[0,0,1]
	v_pk_fma_f32 v[112:113], v[106:107], v[108:109], v[112:113] op_sel_hi:[0,1,1]
	v_perm_b32 v84, v4, v0, s37
	v_mov_b32_e32 v114, v116
	v_mov_b32_e32 v115, v113
	v_mul_f32_e32 v0, v105, v113
	v_pk_fma_f32 v[118:119], v[108:109], v[114:115], v[0:1] op_sel_hi:[1,1,0] neg_lo:[0,0,1] neg_hi:[0,0,1]
	v_mul_f32_e32 v0, v106, v113
	v_pk_fma_f32 v[120:121], v[110:111], v[114:115], v[0:1] op_sel_hi:[1,1,0]
	v_mul_f32_e32 v0, v89, v100
	v_pk_mul_f32 v[90:91], v[90:91], v[102:103]
	v_fmac_f32_e32 v0, v98, v97
	v_sub_f32_e32 v4, v90, v91
	v_and_b32_e32 v125, 0xffff0000, v92
	v_lshlrev_b32_e32 v124, 16, v92
	v_and_b32_e32 v135, 0xffff0000, v93
	v_lshlrev_b32_e32 v134, 16, v93
	v_cndmask_b32_e32 v4, v4, v100, vcc
	v_cndmask_b32_e32 v0, v0, v97, vcc
	v_and_b32_e32 v123, 0xffff0000, v94
	v_lshlrev_b32_e32 v122, 16, v94
	v_and_b32_e32 v133, 0xffff0000, v95
	v_lshlrev_b32_e32 v132, 16, v95
	v_xor_b32_e32 v93, 0x80000000, v135
	v_xor_b32_e32 v92, 0x80000000, v134
	v_xor_b32_e32 v95, 0x80000000, v125
	v_xor_b32_e32 v94, 0x80000000, v124
	v_cndmask_b32_e64 v4, v4, v98, s[2:3]
	v_cndmask_b32_e64 v0, v0, v89, s[2:3]
	v_pk_fma_f32 v[92:93], v[92:93], 0, v[132:133] op_sel_hi:[1,0,1]
	v_pk_fma_f32 v[94:95], v[94:95], 0, v[122:123] op_sel_hi:[1,0,1]
	v_perm_b32 v85, v16, v8, s37
	v_mov_b32_e32 v86, v12
	v_mov_b32_e32 v87, v12
	v_cndmask_b32_e64 v88, v4, 1.0, s[8:9]
	v_cndmask_b32_e64 v91, v0, 0, s[8:9]
	v_cvt_pk_bf16_f32 v0, v94, s0
	v_cvt_pk_bf16_f32 v4, v95, s0
	v_cvt_pk_bf16_f32 v8, v92, s0
	v_cvt_pk_bf16_f32 v12, v93, s0
	v_pk_fma_f32 v[94:95], v[132:133], 0, v[134:135] op_sel_hi:[1,0,1]
	v_pk_fma_f32 v[96:97], v[122:123], 0, v[124:125] op_sel_hi:[1,0,1]
	v_pk_mul_f32 v[98:99], v[104:105], v[134:135] op_sel:[1,0]
	v_perm_b32 v93, v12, v8, s37
	v_perm_b32 v92, v4, v0, s37
	v_cvt_pk_bf16_f32 v0, v96, s0
	v_cvt_pk_bf16_f32 v4, v97, s0
	v_cvt_pk_bf16_f32 v8, v94, s0
	v_cvt_pk_bf16_f32 v12, v95, s0
	v_pk_mul_f32 v[96:97], v[104:105], v[124:125] op_sel:[1,0]
	v_pk_fma_f32 v[98:99], v[106:107], v[132:133], v[98:99] op_sel_hi:[0,1,1] neg_lo:[0,0,1] neg_hi:[0,0,1]
	v_pk_mul_f32 v[100:101], v[104:105], v[132:133] op_sel:[1,0]
	v_perm_b32 v95, v12, v8, s37
	v_pk_fma_f32 v[96:97], v[106:107], v[122:123], v[96:97] op_sel_hi:[0,1,1] neg_lo:[0,0,1] neg_hi:[0,0,1]
	v_cvt_pk_bf16_f32 v8, v98, s0
	v_cvt_pk_bf16_f32 v12, v99, s0
	v_pk_mul_f32 v[98:99], v[104:105], v[122:123] op_sel:[1,0]
	v_pk_fma_f32 v[100:101], v[106:107], v[134:135], v[100:101] op_sel_hi:[0,1,1]
	v_perm_b32 v94, v4, v0, s37
	v_cvt_pk_bf16_f32 v0, v96, s0
	v_cvt_pk_bf16_f32 v4, v97, s0
	v_perm_b32 v97, v12, v8, s37
	v_pk_fma_f32 v[98:99], v[106:107], v[124:125], v[98:99] op_sel_hi:[0,1,1]
	v_cvt_pk_bf16_f32 v8, v100, s0
	v_cvt_pk_bf16_f32 v12, v101, s0
	v_pk_mul_f32 v[100:101], v[112:113], v[124:125] op_sel:[1,0]
	v_perm_b32 v96, v4, v0, s37
	v_cvt_pk_bf16_f32 v0, v98, s0
	v_cvt_pk_bf16_f32 v4, v99, s0
	v_pk_fma_f32 v[100:101], v[116:117], v[122:123], v[100:101] op_sel_hi:[0,1,1] neg_lo:[0,0,1] neg_hi:[0,0,1]
	v_perm_b32 v98, v4, v0, s37
	v_cvt_pk_bf16_f32 v0, v100, s0
	v_cvt_pk_bf16_f32 v4, v101, s0
	s_mul_i32 s2, s43, 0xfffffbc0
	v_perm_b32 v100, v4, v0, s37
	v_or_b32_e32 v0, s2, v127
	s_cselect_b32 s2, s47, s48
	v_add_u32_e32 v106, s2, v0
	v_or_b32_e32 v110, 16, v106
	v_ashrrev_i32_e32 v111, 31, v110
	v_ashrrev_i32_e32 v107, 31, v106
	v_lshlrev_b64 v[110:111], 12, v[110:111]
	v_lshlrev_b64 v[108:109], 12, v[106:107]
	v_lshl_add_u64 v[136:137], v[18:19], 0, v[110:111]
	v_or_b32_e32 v110, 32, v106
	v_or_b32_e32 v106, 48, v106
	v_pk_mul_f32 v[102:103], v[112:113], v[134:135] op_sel:[1,0]
	v_ashrrev_i32_e32 v111, 31, v110
	v_ashrrev_i32_e32 v107, 31, v106
	v_pk_fma_f32 v[102:103], v[116:117], v[132:133], v[102:103] op_sel_hi:[0,1,1] neg_lo:[0,0,1] neg_hi:[0,0,1]
	v_lshl_add_u64 v[108:109], v[18:19], 0, v[108:109]
	v_lshlrev_b64 v[110:111], 12, v[110:111]
	v_lshlrev_b64 v[106:107], 12, v[106:107]
	v_perm_b32 v99, v12, v8, s37
	v_cvt_pk_bf16_f32 v8, v102, s0
	v_cvt_pk_bf16_f32 v12, v103, s0
	v_pk_mul_f32 v[102:103], v[112:113], v[122:123] op_sel:[1,0]
	v_pk_mul_f32 v[104:105], v[112:113], v[132:133] op_sel:[1,0]
	v_lshl_add_u64 v[138:139], v[18:19], 0, v[110:111]
	v_lshl_add_u64 v[106:107], v[18:19], 0, v[106:107]
	s_waitcnt vmcnt(0)
; template <int DIR>
; __device__ __forceinline__ void s5_local_dir(const bf16_t* UZ, unsigned char* ws, int gw, int NGW, int lane) {
;     ...
;     const int qd = gw >> 7, b = qd >> 2, q = qd & 3;
;     if (qd >= 16) return;
;     const int c0 = 17 * q, c1 = q < 3 ? c0 + 17 : 67;
;     float Rr[4] = {0.f, 0.f, 0.f, 0.f}, Ri[4] = {0.f, 0.f, 0.f, 0.f};
;     float* ebase = E + ((size_t)((b * 2 + DIR) * 64 + g) * NCHUNK) * 128;
;     bf16x4 Un[4];
;     load_uf(Un, UZ, chunk_rowbase(b, DIR, c0), g, lane);
;     for (int c = c0; c < c1; ++c) {
;         bf16x4 Uf[4];
; #pragma unroll
;         for (int m = 0; m < 4; ++m) Uf[m] = Un[m];
;         if (c + 1 < c1) load_uf(Un, UZ, chunk_rowbase(b, DIR, c + 1), g, lane);
;         float* e = ebase + (size_t)c * 128;
; #pragma unroll
;         for (int t = 0; t < 4; ++t) {
;             f32x4 cr = {0.f, 0.f, 0.f, 0.f}, ci = {0.f, 0.f, 0.f, 0.f};
; #pragma unroll
;             for (int m = 0; m < 4; ++m) {
;                 cr = __builtin_amdgcn_mfma_f32_16x16x16bf16_1k(Uf[m], Bre[m][t], cr, 0, 0, 0);
;                 ci = __builtin_amdgcn_mfma_f32_16x16x16bf16_1k(Uf[m], Bim[m][t], ci, 0, 0, 0);
;             }
;             f32x2 s2 = {DIR ? cr[3] : cr[0], DIR ? ci[3] : ci[0]};
; #pragma unroll
;             for (int ii = 1; ii < 4; ++ii) { const int i = DIR ? 3 - ii : ii;
;                 s2 = cmac(s2, (f32x2){a1r[t], a1r[t]}, (f32x2){-a1i[t], a1i[t]}, (f32x2){cr[i], ci[i]}); }
;             s2 = cmac(s2, (f32x2){wr_[t], wr_[t]}, (f32x2){-wi_[t], wi_[t]}, (f32x2){0.f, 0.f});
;             float sr = s2.x, si = s2.y;
;             sr += __shfl_xor(sr, 16); si += __shfl_xor(si, 16); sr += __shfl_xor(sr, 32); si += __shfl_xor(si, 32);
;             if (fq == 0) { e[16 * t + fr] = Rr[t]; e[64 + 16 * t + fr] = Ri[t]; }
;             const float nr = fmaf(a64r[t], Rr[t], fmaf(-a64i[t], Ri[t], sr)), ni = fmaf(a64r[t], Ri[t], fmaf(a64i[t], Rr[t], si)); Rr[t] = nr; Ri[t] = ni;
	v_mov_b64_e32 v[110:111], v[152:153]
	v_mov_b64_e32 v[112:113], v[154:155]
	v_mov_b64_e32 v[114:115], v[156:157]
	v_mov_b64_e32 v[108:109], v[158:159]
	v_pk_fma_f32 v[104:105], v[116:117], v[134:135], v[104:105] op_sel_hi:[0,1,1]
	v_pk_mul_f32 v[106:107], v[120:121], v[134:135] op_sel_hi:[0,1]
	v_perm_b32 v101, v12, v8, s37
	v_pk_fma_f32 v[102:103], v[116:117], v[124:125], v[102:103] op_sel_hi:[0,1,1]
	v_cvt_pk_bf16_f32 v8, v104, s0
	v_cvt_pk_bf16_f32 v12, v105, s0
	v_pk_mul_f32 v[104:105], v[120:121], v[124:125] op_sel_hi:[0,1]
	v_pk_fma_f32 v[106:107], v[118:119], v[132:133], v[106:107] op_sel_hi:[0,1,1] neg_lo:[0,0,1] neg_hi:[0,0,1]
	v_cvt_pk_bf16_f32 v0, v102, s0
	v_cvt_pk_bf16_f32 v4, v103, s0
	v_perm_b32 v103, v12, v8, s37
	v_pk_fma_f32 v[104:105], v[118:119], v[122:123], v[104:105] op_sel_hi:[0,1,1] neg_lo:[0,0,1] neg_hi:[0,0,1]
	v_cvt_pk_bf16_f32 v8, v106, s0
	v_cvt_pk_bf16_f32 v12, v107, s0
	v_pk_mul_f32 v[106:107], v[120:121], v[122:123] op_sel_hi:[0,1]
	v_perm_b32 v102, v4, v0, s37
	v_cvt_pk_bf16_f32 v0, v104, s0
	v_cvt_pk_bf16_f32 v4, v105, s0
	v_pk_fma_f32 v[106:107], v[118:119], v[124:125], v[106:107] op_sel_hi:[0,1,1]
	v_perm_b32 v104, v4, v0, s37
	v_pk_mul_f32 v[116:117], v[120:121], v[132:133] op_sel_hi:[0,1]
	v_cvt_pk_bf16_f32 v0, v106, s0
	v_cvt_pk_bf16_f32 v4, v107, s0
	s_add_i32 s2, s45, s44
	v_pk_fma_f32 v[116:117], v[118:119], v[134:135], v[116:117] op_sel_hi:[0,1,1]
	v_perm_b32 v106, v4, v0, s37
	v_mbcnt_lo_u32_b32 v0, -1, 0
	s_add_i32 s2, s2, 64
	s_bfe_u32 s36, s40, 0x20007
	v_perm_b32 v105, v12, v8, s37
	v_cvt_pk_bf16_f32 v8, v116, s0
	v_cvt_pk_bf16_f32 v12, v117, s0
	v_mbcnt_hi_u32_b32 v0, -1, v0
	s_mul_hi_i32 s3, s2, 0x8800
	s_mul_i32 s2, s2, 0x8800
	s_mulk_i32 s36, 0x2200
	v_perm_b32 v107, v12, v8, s37
	v_and_b32_e32 v8, 64, v0
	s_add_u32 s2, s2, s36
	v_xor_b32_e32 v4, 16, v0
	v_add_u32_e32 v8, 64, v8
	s_addc_u32 s3, s3, 0
	v_cmp_lt_i32_e32 vcc, v4, v8
	s_add_u32 s2, s30, s2
	v_lshlrev_b32_e32 v16, 2, v126
	v_cndmask_b32_e32 v4, v0, v4, vcc
	s_addc_u32 s3, s31, s3
	v_lshlrev_b32_e32 v131, 2, v4
	v_xor_b32_e32 v4, 32, v0
	v_lshl_add_u64 v[116:117], s[2:3], 0, v[16:17]
	s_mov_b64 s[2:3], 0x1700100
	v_cmp_lt_i32_e32 vcc, v4, v8
	v_lshl_add_u64 v[116:117], v[116:117], 0, s[2:3]
	s_mul_i32 s2, s43, 0x440
	v_cndmask_b32_e32 v0, v0, v4, vcc
	v_subrev_u32_e32 v16, s2, v127
	v_lshlrev_b32_e32 v132, 2, v0
	v_xor_b32_e32 v0, 0x80000000, v1
	v_mov_b32_e32 v23, v22
	v_xor_b32_e32 v24, 0x80000000, v25
	v_xor_b32_e32 v4, 0x80000000, v5
	v_mov_b32_e32 v45, v44
	v_xor_b32_e32 v46, 0x80000000, v47
	v_xor_b32_e32 v8, 0x80000000, v9
	v_mov_b32_e32 v67, v66
	v_xor_b32_e32 v68, 0x80000000, v69
	v_xor_b32_e32 v12, 0x80000000, v13
	v_mov_b32_e32 v89, v88
	v_xor_b32_e32 v90, 0x80000000, v91
	v_subrev_u32_e32 v16, 32, v16
	s_mov_b64 s[2:3], 0x200
	v_mov_b32_e32 v137, v17
	v_mov_b32_e32 v135, v17
	v_mov_b32_e32 v133, v17
	v_mov_b32_e32 v139, v17
	v_mov_b32_e32 v138, v17
	v_mov_b32_e32 v136, v17
	v_mov_b32_e32 v134, v17
	v_and_b32_e32 v244, 16, v126
	v_and_b32_e32 v245, 32, v126
	v_cmp_ne_u32_e64 s[96:97], 0, v244
	v_cmp_ne_u32_e32 vcc, 0, v245
	s_nop 1
	v_cndmask_b32_e32 v244, v2, v10, vcc
	v_cndmask_b32_e32 v245, v6, v14, vcc
	v_cndmask_b32_e64 v242, v244, v245, s[96:97]
	v_cndmask_b32_e32 v244, v3, v11, vcc
	v_cndmask_b32_e32 v245, v7, v15, vcc
	v_cndmask_b32_e64 v243, v244, v245, s[96:97]

; template <int DIR>
; __device__ __forceinline__ void s5_local_dir(const bf16_t* UZ, unsigned char* ws, int gw, int NGW, int lane) {
;     float* E = (float*)(ws + WS_E);
;     const int pair = gw & 127, g = pair & 63, fr = lane & 15, fq = lane >> 4;
;     const bf16_t* Bb = (const bf16_t*)(ws + WS_BB) + (size_t)pair * 128 * 16;
;     bf16x4 Bre[4][4], Bim[4][4]; float a1r[4], a1i[4], a64r[4], a64i[4], wr_[4], wi_[4];
; #pragma unroll
;     for (int t = 0; t < 4; ++t) {
;         const int p = 16 * t + fr;
;         const bf16x4 b_re = *(const bf16x4*)(Bb + (2 * p) * 16 + 4 * fq), b_im = *(const bf16x4*)(Bb + (2 * p + 1) * 16 + 4 * fq);
;         const f32x4 ap = ((const f32x4*)(ws + WS_APOW))[pair * 64 + p];
;         const float ar = ap.x, ai = ap.y;
;         float r2 = ar, i2 = ai; cmul(r2, i2, ar, ai);
;         float r4 = r2, i4 = i2; cmul(r4, i4, r2, i2);
;         float r8 = r4, i8 = i4; cmul(r8, i8, r4, i4);
;         float r12 = r8, i12 = i8; cmul(r12, i12, r4, i4);
;         float r16 = r8, i16 = i8; cmul(r16, i16, r8, i8);
;         float r32 = r16, i32 = i16; cmul(r32, i32, r16, i16);
;         float r48 = r32, i48 = i32; cmul(r48, i48, r16, i16);
;         a1r[t] = ar; a1i[t] = ai; a64r[t] = ap.z; a64i[t] = ap.w;
;         const int e = DIR ? fq : 3 - fq;
;         wr_[t] = e == 0 ? 1.f : e == 1 ? r4 : e == 2 ? r8 : r12; wi_[t] = e == 0 ? 0.f : e == 1 ? i4 : e == 2 ? i8 : i12;
; #pragma unroll
;         for (int m = 0; m < 4; ++m) {
;             const int em = DIR ? m : 3 - m;
;             const float pr = em == 0 ? 1.f : em == 1 ? r16 : em == 2 ? r32 : r48, pi = em == 0 ? 0.f : em == 1 ? i16 : em == 2 ? i32 : i48;
;             Bre[m][t] = cscale_bf(b_re, b_im, pr, pi, false); Bim[m][t] = cscale_bf(b_re, b_im, pr, pi, true);
;         }
;     }
;     const int qd = gw >> 7, b = qd >> 2, q = qd & 3;
;     if (qd >= 16) return;
;     const int c0 = 17 * q, c1 = q < 3 ? c0 + 17 : 67;
;     float Rr[4] = {0.f, 0.f, 0.f, 0.f}, Ri[4] = {0.f, 0.f, 0.f, 0.f};
;     float* ebase = E + ((size_t)((b * 2 + DIR) * 64 + g) * NCHUNK) * 128;
;     bf16x4 Un[4];
;     load_uf(Un, UZ, chunk_rowbase(b, DIR, c0), g, lane);
.LBB0_669:
	s_mul_i32 s24, s37, 17
	s_add_i32 s4, s24, 17
	s_cmp_lg_u32 s37, 3
	s_cselect_b64 s[8:9], -1, 0
	s_and_b64 s[2:3], s[8:9], exec
	s_cselect_b32 s39, s4, 0x43
	s_lshl_b32 s38, s23, 7
	v_mov_b32_e32 v115, 0
	v_mov_b32_e32 v240, 0
	v_mov_b32_e32 v241, 0
	s_cmp_ge_u32 s24, s39
	v_mov_b32_e32 v114, 0
	v_mov_b32_e32 v112, 0
	v_mov_b32_e32 v110, 0
	v_mov_b32_e32 v113, 0
	v_mov_b32_e32 v111, 0
	v_mov_b32_e32 v109, 0
	v_mov_b32_e32 v108, 0
	s_cbranch_scc1 .LBB0_702
	s_lshl_b32 s100, s36, 5
	s_add_u32 s100, s18, s100
	s_addc_u32 s101, s19, 0
	v_add_u32_e32 v160, s25, v127
	v_ashrrev_i32_e32 v161, 31, v160
	v_lshlrev_b64 v[162:163], 12, v[160:161]
	v_lshrrev_b32_e32 v164, 1, v192
	v_and_b32_e32 v164, 24, v164
	v_mov_b32_e32 v165, 0
	v_lshl_add_u64 v[162:163], s[100:101], 0, v[162:163]
	v_lshl_add_u64 v[162:163], v[162:163], 0, v[164:165]
	s_mov_b32 s98, 0x10000
	s_mov_b32 s99, 0
	v_lshl_add_u64 v[164:165], v[162:163], 0, s[98:99]
	v_lshl_add_u64 v[166:167], v[164:165], 0, s[98:99]
	v_lshl_add_u64 v[168:169], v[166:167], 0, s[98:99]
	global_load_dwordx2 v[152:153], v[162:163], off
	global_load_dwordx2 v[154:155], v[164:165], off
	global_load_dwordx2 v[156:157], v[166:167], off
	global_load_dwordx2 v[158:159], v[168:169], off
	s_waitcnt vmcnt(13)
	v_pk_mul_f32 v[22:23], v[0:1], v[0:1] op_sel:[1,1] op_sel_hi:[1,0]
	s_lshl_b32 s2, s36, 5
	v_pk_fma_f32 v[24:25], v[0:1], v[0:1], v[22:23] op_sel_hi:[1,0,1] neg_lo:[0,0,1] neg_hi:[0,0,1]
	v_pk_fma_f32 v[22:23], v[0:1], v[0:1], v[22:23] op_sel_hi:[1,0,1]
	v_mov_b32_e32 v30, v24
	v_pk_mov_b32 v[32:33], v[22:23], v[24:25] op_sel:[1,0]
	v_mov_b32_e32 v31, v23
	v_pk_mul_f32 v[22:23], v[22:23], v[32:33] op_sel:[1,0]
	v_mov_b32_e32 v18, v0
	v_pk_fma_f32 v[32:33], v[24:25], v[30:31], v[22:23] op_sel_hi:[0,1,1] neg_lo:[0,0,1] neg_hi:[0,0,1]
	v_pk_fma_f32 v[22:23], v[24:25], v[30:31], v[22:23] op_sel_hi:[0,1,1]
	v_pk_mov_b32 v[30:31], v[22:23], v[32:33] op_sel:[1,0]
	v_mov_b32_e32 v24, v32
	v_mov_b32_e32 v25, v23
	v_pk_mul_f32 v[30:31], v[22:23], v[30:31] op_sel:[1,0]
	v_mov_b32_e32 v19, v0
	v_pk_fma_f32 v[34:35], v[32:33], v[24:25], v[30:31] op_sel_hi:[0,1,1] neg_lo:[0,0,1] neg_hi:[0,0,1]
	v_pk_fma_f32 v[30:31], v[32:33], v[24:25], v[30:31] op_sel_hi:[0,1,1]
	v_mov_b32_e32 v35, v31
	v_pk_mul_f32 v[36:37], v[34:35], v[34:35]
	v_pk_mul_f32 v[38:39], v[30:31], v[34:35] op_sel:[1,0] op_sel_hi:[0,1]
	v_mov_b32_e32 v40, v36
	v_mov_b32_e32 v41, v38
	v_pk_mov_b32 v[36:37], v[36:37], v[38:39] op_sel:[1,0]
	s_add_u32 s2, s18, s2
	v_pk_add_f32 v[38:39], v[40:41], v[36:37] neg_lo:[0,1] neg_hi:[0,1]
	v_pk_add_f32 v[36:37], v[40:41], v[36:37]
	v_mov_b32_e32 v40, v38
	v_mov_b32_e32 v41, v37
	v_pk_mul_f32 v[44:45], v[40:41], v[40:41]
	v_pk_mul_f32 v[46:47], v[36:37], v[40:41] op_sel:[1,0] op_sel_hi:[0,1]
	v_mov_b32_e32 v52, v44
	v_mov_b32_e32 v53, v46
	v_pk_mov_b32 v[44:45], v[44:45], v[46:47] op_sel:[1,0]
	v_lshrrev_b32_e32 v16, 1, v192
	v_pk_add_f32 v[46:47], v[52:53], v[44:45] neg_lo:[0,1] neg_hi:[0,1]
	v_pk_add_f32 v[44:45], v[52:53], v[44:45]
	v_mov_b32_e32 v52, v46
	v_mov_b32_e32 v53, v45
	v_mul_f32_e32 v0, v37, v45
	v_pk_mov_b32 v[42:43], v[36:37], v[38:39] op_sel:[1,0]
	v_pk_fma_f32 v[40:41], v[40:41], v[52:53], v[0:1] op_sel_hi:[1,1,0] neg_lo:[0,0,1] neg_hi:[0,0,1]
	v_mul_f32_e32 v0, v38, v45
	s_addc_u32 s3, s19, 0
	v_and_b32_e32 v20, 24, v16
	v_mov_b32_e32 v21, 0
	v_pk_fma_f32 v[42:43], v[42:43], v[52:53], v[0:1] op_sel_hi:[1,1,0]
	v_mul_f32_e32 v0, v23, v34
	v_pk_mul_f32 v[24:25], v[24:25], v[34:35]
	v_and_b32_e32 v59, 0xffff0000, v27
	v_lshlrev_b32_e32 v58, 16, v27
	v_lshl_add_u64 v[16:17], s[2:3], 0, v[20:21]
	v_fmac_f32_e32 v0, v32, v31
	v_sub_f32_e32 v20, v24, v25
	v_cmp_eq_u32_e32 vcc, 1, v128
	v_and_b32_e32 v53, 0xffff0000, v28
	v_lshlrev_b32_e32 v52, 16, v28
	v_and_b32_e32 v55, 0xffff0000, v26
	v_lshlrev_b32_e32 v54, 16, v26
	v_and_b32_e32 v57, 0xffff0000, v29
	v_lshlrev_b32_e32 v56, 16, v29
	v_pk_mul_f32 v[28:29], v[42:43], v[58:59] op_sel_hi:[0,1]
	v_cndmask_b32_e32 v20, v20, v34, vcc
	v_cmp_eq_u32_e64 s[2:3], 2, v128
	v_cndmask_b32_e32 v0, v0, v31, vcc
	v_pk_mul_f32 v[26:27], v[42:43], v[54:55] op_sel_hi:[0,1]
	v_pk_fma_f32 v[28:29], v[40:41], v[56:57], v[28:29] op_sel_hi:[0,1,1] neg_lo:[0,0,1] neg_hi:[0,0,1]
	v_pk_mul_f32 v[30:31], v[42:43], v[56:57] op_sel_hi:[0,1]
	v_cndmask_b32_e64 v20, v20, v32, s[2:3]
	v_cndmask_b32_e64 v0, v0, v23, s[2:3]
	v_cmp_eq_u32_e64 s[4:5], 3, v128
	v_pk_fma_f32 v[26:27], v[40:41], v[52:53], v[26:27] op_sel_hi:[0,1,1] neg_lo:[0,0,1] neg_hi:[0,0,1]
	v_cvt_pk_bf16_f32 v23, v28, s0
	v_cvt_pk_bf16_f32 v24, v29, s0
	s_mov_b32 s41, 0x5040100
	v_pk_mul_f32 v[28:29], v[42:43], v[52:53] op_sel_hi:[0,1]
	v_pk_fma_f32 v[30:31], v[40:41], v[58:59], v[30:31] op_sel_hi:[0,1,1]
	v_pk_mul_f32 v[32:33], v[44:45], v[58:59] op_sel:[1,0]
	v_cndmask_b32_e64 v22, v20, 1.0, s[4:5]
	v_cndmask_b32_e64 v25, v0, 0, s[4:5]
	v_cvt_pk_bf16_f32 v0, v26, s0
	v_cvt_pk_bf16_f32 v20, v27, s0
	v_perm_b32 v27, v24, v23, s41
	v_pk_fma_f32 v[28:29], v[40:41], v[54:55], v[28:29] op_sel_hi:[0,1,1]
	v_cvt_pk_bf16_f32 v23, v30, s0
	v_cvt_pk_bf16_f32 v24, v31, s0
	v_pk_mul_f32 v[30:31], v[44:45], v[54:55] op_sel:[1,0]
	v_pk_fma_f32 v[32:33], v[46:47], v[56:57], v[32:33] op_sel_hi:[0,1,1] neg_lo:[0,0,1] neg_hi:[0,0,1]
	v_pk_mul_f32 v[34:35], v[44:45], v[56:57] op_sel:[1,0]
	v_perm_b32 v26, v20, v0, s41
	v_cvt_pk_bf16_f32 v0, v28, s0
	v_cvt_pk_bf16_f32 v20, v29, s0
	v_perm_b32 v29, v24, v23, s41
	v_pk_fma_f32 v[30:31], v[46:47], v[52:53], v[30:31] op_sel_hi:[0,1,1] neg_lo:[0,0,1] neg_hi:[0,0,1]
	v_cvt_pk_bf16_f32 v23, v32, s0
	v_cvt_pk_bf16_f32 v24, v33, s0
	v_pk_mul_f32 v[32:33], v[44:45], v[52:53] op_sel:[1,0]
	v_pk_fma_f32 v[34:35], v[46:47], v[58:59], v[34:35] op_sel_hi:[0,1,1]
	v_pk_mul_f32 v[40:41], v[36:37], v[58:59] op_sel:[1,0]
	v_perm_b32 v28, v20, v0, s41
	v_cvt_pk_bf16_f32 v0, v30, s0
	v_cvt_pk_bf16_f32 v20, v31, s0
	v_perm_b32 v31, v24, v23, s41
	v_pk_fma_f32 v[32:33], v[46:47], v[54:55], v[32:33] op_sel_hi:[0,1,1]
	v_cvt_pk_bf16_f32 v23, v34, s0
	v_cvt_pk_bf16_f32 v24, v35, s0
	v_pk_fma_f32 v[40:41], v[38:39], v[56:57], v[40:41] op_sel_hi:[0,1,1] neg_lo:[0,0,1] neg_hi:[0,0,1]
	s_waitcnt vmcnt(10)
; template <int DIR>
; __device__ __forceinline__ void s5_local_dir(const bf16_t* UZ, unsigned char* ws, int gw, int NGW, int lane) {
;     ...
;     for (int t = 0; t < 4; ++t) {
;         const int p = 16 * t + fr;
;         const bf16x4 b_re = *(const bf16x4*)(Bb + (2 * p) * 16 + 4 * fq), b_im = *(const bf16x4*)(Bb + (2 * p + 1) * 16 + 4 * fq);
;         const f32x4 ap = ((const f32x4*)(ws + WS_APOW))[pair * 64 + p];
;         const float ar = ap.x, ai = ap.y;
;         float r2 = ar, i2 = ai; cmul(r2, i2, ar, ai);
;         float r4 = r2, i4 = i2; cmul(r4, i4, r2, i2);
;         float r8 = r4, i8 = i4; cmul(r8, i8, r4, i4);
;         float r12 = r8, i12 = i8; cmul(r12, i12, r4, i4);
;         float r16 = r8, i16 = i8; cmul(r16, i16, r8, i8);
;         float r32 = r16, i32 = i16; cmul(r32, i32, r16, i16);
;         float r48 = r32, i48 = i32; cmul(r48, i48, r16, i16);
;         a1r[t] = ar; a1i[t] = ai; a64r[t] = ap.z; a64i[t] = ap.w;
;         const int e = DIR ? fq : 3 - fq;
;         wr_[t] = e == 0 ? 1.f : e == 1 ? r4 : e == 2 ? r8 : r12; wi_[t] = e == 0 ? 0.f : e == 1 ? i4 : e == 2 ? i8 : i12;
; #pragma unroll
;         for (int m = 0; m < 4; ++m) {
;             const int em = DIR ? m : 3 - m;
;             const float pr = em == 0 ? 1.f : em == 1 ? r16 : em == 2 ? r32 : r48, pi = em == 0 ? 0.f : em == 1 ? i16 : em == 2 ? i32 : i48;
;             Bre[m][t] = cscale_bf(b_re, b_im, pr, pi, false); Bim[m][t] = cscale_bf(b_re, b_im, pr, pi, true);
;         }
	v_pk_mul_f32 v[44:45], v[4:5], v[4:5] op_sel:[1,1] op_sel_hi:[1,0]
	v_perm_b32 v30, v20, v0, s41
	v_cvt_pk_bf16_f32 v20, v33, s0
	v_perm_b32 v33, v24, v23, s41
	v_pk_mul_f32 v[34:35], v[36:37], v[54:55] op_sel:[1,0]
	v_cvt_pk_bf16_f32 v23, v40, s0
	v_cvt_pk_bf16_f32 v24, v41, s0
	v_pk_mul_f32 v[40:41], v[36:37], v[52:53] op_sel:[1,0]
	v_pk_mul_f32 v[36:37], v[36:37], v[56:57] op_sel:[1,0]
	v_pk_fma_f32 v[46:47], v[4:5], v[4:5], v[44:45] op_sel_hi:[1,0,1] neg_lo:[0,0,1] neg_hi:[0,0,1]
	v_pk_fma_f32 v[44:45], v[4:5], v[4:5], v[44:45] op_sel_hi:[1,0,1]
	v_pk_fma_f32 v[34:35], v[38:39], v[52:53], v[34:35] op_sel_hi:[0,1,1] neg_lo:[0,0,1] neg_hi:[0,0,1]
	v_pk_fma_f32 v[36:37], v[38:39], v[58:59], v[36:37] op_sel_hi:[0,1,1]
	v_pk_fma_f32 v[38:39], v[38:39], v[54:55], v[40:41] op_sel_hi:[0,1,1]
	v_xor_b32_e32 v41, 0x80000000, v55
	v_xor_b32_e32 v40, 0x80000000, v54
	v_pk_fma_f32 v[42:43], v[52:53], 0, v[54:55] op_sel_hi:[1,0,1]
	v_pk_mov_b32 v[54:55], v[44:45], v[46:47] op_sel:[1,0]
	v_pk_fma_f32 v[40:41], v[40:41], 0, v[52:53] op_sel_hi:[1,0,1]
	v_mov_b32_e32 v52, v46
	v_mov_b32_e32 v53, v45
	v_pk_mul_f32 v[44:45], v[44:45], v[54:55] op_sel:[1,0]
	v_cvt_pk_bf16_f32 v0, v32, s0
	v_pk_fma_f32 v[54:55], v[46:47], v[52:53], v[44:45] op_sel_hi:[0,1,1] neg_lo:[0,0,1] neg_hi:[0,0,1]
	v_pk_fma_f32 v[44:45], v[46:47], v[52:53], v[44:45] op_sel_hi:[0,1,1]
	v_perm_b32 v32, v20, v0, s41
	v_cvt_pk_bf16_f32 v0, v34, s0
	v_cvt_pk_bf16_f32 v20, v35, s0
	v_pk_mov_b32 v[52:53], v[44:45], v[54:55] op_sel:[1,0]
	v_perm_b32 v34, v20, v0, s41
	v_cvt_pk_bf16_f32 v0, v38, s0
	v_cvt_pk_bf16_f32 v20, v39, s0
	v_xor_b32_e32 v39, 0x80000000, v59
	v_xor_b32_e32 v38, 0x80000000, v58
	v_mov_b32_e32 v46, v54
	v_mov_b32_e32 v47, v45
	v_pk_mul_f32 v[52:53], v[44:45], v[52:53] op_sel:[1,0]
	v_perm_b32 v35, v24, v23, s41
	v_cvt_pk_bf16_f32 v23, v36, s0
	v_perm_b32 v36, v20, v0, s41
	v_pk_fma_f32 v[38:39], v[38:39], 0, v[56:57] op_sel_hi:[1,0,1]
	v_cvt_pk_bf16_f32 v0, v40, s0
	v_cvt_pk_bf16_f32 v20, v41, s0
	v_pk_fma_f32 v[40:41], v[56:57], 0, v[58:59] op_sel_hi:[1,0,1]
	v_pk_fma_f32 v[56:57], v[54:55], v[46:47], v[52:53] op_sel_hi:[0,1,1] neg_lo:[0,0,1] neg_hi:[0,0,1]
	v_pk_fma_f32 v[52:53], v[54:55], v[46:47], v[52:53] op_sel_hi:[0,1,1]
	v_mov_b32_e32 v57, v53
	v_pk_mul_f32 v[58:59], v[56:57], v[56:57]
	v_pk_mul_f32 v[60:61], v[52:53], v[56:57] op_sel:[1,0] op_sel_hi:[0,1]
	v_mov_b32_e32 v62, v58
	v_mov_b32_e32 v63, v60
	v_pk_mov_b32 v[58:59], v[58:59], v[60:61] op_sel:[1,0]
	v_cvt_pk_bf16_f32 v24, v37, s0
	v_pk_add_f32 v[60:61], v[62:63], v[58:59] neg_lo:[0,1] neg_hi:[0,1]
	v_pk_add_f32 v[58:59], v[62:63], v[58:59]
	v_mov_b32_e32 v62, v60
	v_mov_b32_e32 v63, v59
	v_pk_mul_f32 v[66:67], v[62:63], v[62:63]
	v_pk_mul_f32 v[68:69], v[58:59], v[62:63] op_sel:[1,0] op_sel_hi:[0,1]
	v_mov_b32_e32 v74, v66
	v_mov_b32_e32 v75, v68
	v_pk_mov_b32 v[66:67], v[66:67], v[68:69] op_sel:[1,0]
	v_perm_b32 v37, v24, v23, s41
	v_cvt_pk_bf16_f32 v23, v38, s0
	v_cvt_pk_bf16_f32 v24, v39, s0
	v_perm_b32 v38, v20, v0, s41
	v_cvt_pk_bf16_f32 v0, v42, s0
	v_cvt_pk_bf16_f32 v20, v43, s0
	v_pk_add_f32 v[68:69], v[74:75], v[66:67] neg_lo:[0,1] neg_hi:[0,1]
	v_pk_add_f32 v[66:67], v[74:75], v[66:67]
	v_perm_b32 v39, v24, v23, s41
	v_cvt_pk_bf16_f32 v23, v40, s0
	v_perm_b32 v40, v20, v0, s41
	v_mov_b32_e32 v74, v68
	v_mov_b32_e32 v75, v67
	v_mul_f32_e32 v0, v59, v67
	v_pk_mov_b32 v[64:65], v[58:59], v[60:61] op_sel:[1,0]
	v_pk_fma_f32 v[62:63], v[62:63], v[74:75], v[0:1] op_sel_hi:[1,1,0] neg_lo:[0,0,1] neg_hi:[0,0,1]
	v_mul_f32_e32 v0, v60, v67
	v_pk_fma_f32 v[64:65], v[64:65], v[74:75], v[0:1] op_sel_hi:[1,1,0]
	v_mul_f32_e32 v0, v45, v56
	v_pk_mul_f32 v[46:47], v[46:47], v[56:57]
	v_and_b32_e32 v81, 0xffff0000, v51
	v_lshlrev_b32_e32 v80, 16, v51
	v_mov_b32_e32 v42, v4
	v_mov_b32_e32 v43, v4
	v_fmac_f32_e32 v0, v54, v53
	v_sub_f32_e32 v4, v46, v47
	v_and_b32_e32 v77, 0xffff0000, v50
	v_lshlrev_b32_e32 v76, 16, v50
	v_and_b32_e32 v79, 0xffff0000, v49
	v_lshlrev_b32_e32 v78, 16, v49
	v_pk_mul_f32 v[50:51], v[64:65], v[80:81] op_sel_hi:[0,1]
	v_cvt_pk_bf16_f32 v24, v41, s0
	v_cndmask_b32_e32 v4, v4, v56, vcc
	v_cndmask_b32_e32 v0, v0, v53, vcc
	v_and_b32_e32 v75, 0xffff0000, v48
	v_lshlrev_b32_e32 v74, 16, v48
	v_pk_mul_f32 v[48:49], v[64:65], v[76:77] op_sel_hi:[0,1]
	v_pk_fma_f32 v[50:51], v[62:63], v[78:79], v[50:51] op_sel_hi:[0,1,1] neg_lo:[0,0,1] neg_hi:[0,0,1]
	v_pk_mul_f32 v[52:53], v[64:65], v[78:79] op_sel_hi:[0,1]
	v_perm_b32 v41, v24, v23, s41
	v_cndmask_b32_e64 v4, v4, v54, s[2:3]
	v_cndmask_b32_e64 v0, v0, v45, s[2:3]
	v_pk_fma_f32 v[48:49], v[62:63], v[74:75], v[48:49] op_sel_hi:[0,1,1] neg_lo:[0,0,1] neg_hi:[0,0,1]
	v_cvt_pk_bf16_f32 v20, v50, s0
	v_cvt_pk_bf16_f32 v23, v51, s0
	v_pk_mul_f32 v[50:51], v[64:65], v[74:75] op_sel_hi:[0,1]
	v_pk_fma_f32 v[52:53], v[62:63], v[80:81], v[52:53] op_sel_hi:[0,1,1]
	v_pk_mul_f32 v[54:55], v[66:67], v[80:81] op_sel:[1,0]
	v_cndmask_b32_e64 v44, v4, 1.0, s[4:5]
	v_cndmask_b32_e64 v47, v0, 0, s[4:5]
	v_cvt_pk_bf16_f32 v0, v48, s0
	v_cvt_pk_bf16_f32 v4, v49, s0
	v_perm_b32 v49, v23, v20, s41
	v_pk_fma_f32 v[50:51], v[62:63], v[76:77], v[50:51] op_sel_hi:[0,1,1]
	v_cvt_pk_bf16_f32 v20, v52, s0
	v_cvt_pk_bf16_f32 v23, v53, s0
	v_pk_mul_f32 v[52:53], v[66:67], v[76:77] op_sel:[1,0]
	v_pk_fma_f32 v[54:55], v[68:69], v[78:79], v[54:55] op_sel_hi:[0,1,1] neg_lo:[0,0,1] neg_hi:[0,0,1]
	v_pk_mul_f32 v[56:57], v[66:67], v[78:79] op_sel:[1,0]
	v_perm_b32 v48, v4, v0, s41
	v_cvt_pk_bf16_f32 v0, v50, s0
	v_cvt_pk_bf16_f32 v4, v51, s0
	v_perm_b32 v51, v23, v20, s41
	v_pk_fma_f32 v[52:53], v[68:69], v[74:75], v[52:53] op_sel_hi:[0,1,1] neg_lo:[0,0,1] neg_hi:[0,0,1]
	v_cvt_pk_bf16_f32 v20, v54, s0
	v_cvt_pk_bf16_f32 v23, v55, s0
	v_pk_mul_f32 v[54:55], v[66:67], v[74:75] op_sel:[1,0]
	v_pk_fma_f32 v[56:57], v[68:69], v[80:81], v[56:57] op_sel_hi:[0,1,1]
	v_pk_mul_f32 v[62:63], v[58:59], v[80:81] op_sel:[1,0]
	v_perm_b32 v50, v4, v0, s41
	v_cvt_pk_bf16_f32 v0, v52, s0
	v_cvt_pk_bf16_f32 v4, v53, s0
	v_perm_b32 v53, v23, v20, s41
	v_pk_fma_f32 v[54:55], v[68:69], v[76:77], v[54:55] op_sel_hi:[0,1,1]
	v_cvt_pk_bf16_f32 v20, v56, s0
	v_cvt_pk_bf16_f32 v23, v57, s0
	v_pk_fma_f32 v[62:63], v[60:61], v[78:79], v[62:63] op_sel_hi:[0,1,1] neg_lo:[0,0,1] neg_hi:[0,0,1]
	s_waitcnt vmcnt(7)
; template <int DIR>
; __device__ __forceinline__ void s5_local_dir(const bf16_t* UZ, unsigned char* ws, int gw, int NGW, int lane) {
;     ...
;     for (int t = 0; t < 4; ++t) {
;         const int p = 16 * t + fr;
;         const bf16x4 b_re = *(const bf16x4*)(Bb + (2 * p) * 16 + 4 * fq), b_im = *(const bf16x4*)(Bb + (2 * p + 1) * 16 + 4 * fq);
;         const f32x4 ap = ((const f32x4*)(ws + WS_APOW))[pair * 64 + p];
;         const float ar = ap.x, ai = ap.y;
;         float r2 = ar, i2 = ai; cmul(r2, i2, ar, ai);
;         float r4 = r2, i4 = i2; cmul(r4, i4, r2, i2);
;         float r8 = r4, i8 = i4; cmul(r8, i8, r4, i4);
;         float r12 = r8, i12 = i8; cmul(r12, i12, r4, i4);
;         float r16 = r8, i16 = i8; cmul(r16, i16, r8, i8);
;         float r32 = r16, i32 = i16; cmul(r32, i32, r16, i16);
;         float r48 = r32, i48 = i32; cmul(r48, i48, r16, i16);
;         a1r[t] = ar; a1i[t] = ai; a64r[t] = ap.z; a64i[t] = ap.w;
;         const int e = DIR ? fq : 3 - fq;
;         wr_[t] = e == 0 ? 1.f : e == 1 ? r4 : e == 2 ? r8 : r12; wi_[t] = e == 0 ? 0.f : e == 1 ? i4 : e == 2 ? i8 : i12;
; #pragma unroll
;         for (int m = 0; m < 4; ++m) {
;             const int em = DIR ? m : 3 - m;
;             const float pr = em == 0 ? 1.f : em == 1 ? r16 : em == 2 ? r32 : r48, pi = em == 0 ? 0.f : em == 1 ? i16 : em == 2 ? i32 : i48;
;             Bre[m][t] = cscale_bf(b_re, b_im, pr, pi, false); Bim[m][t] = cscale_bf(b_re, b_im, pr, pi, true);
;         }
	v_pk_mul_f32 v[66:67], v[8:9], v[8:9] op_sel:[1,1] op_sel_hi:[1,0]
	v_perm_b32 v52, v4, v0, s41
	v_cvt_pk_bf16_f32 v4, v55, s0
	v_perm_b32 v55, v23, v20, s41
	v_pk_mul_f32 v[56:57], v[58:59], v[76:77] op_sel:[1,0]
	v_cvt_pk_bf16_f32 v20, v62, s0
	v_cvt_pk_bf16_f32 v23, v63, s0
	v_pk_mul_f32 v[62:63], v[58:59], v[74:75] op_sel:[1,0]
	v_pk_mul_f32 v[58:59], v[58:59], v[78:79] op_sel:[1,0]
	v_pk_fma_f32 v[68:69], v[8:9], v[8:9], v[66:67] op_sel_hi:[1,0,1] neg_lo:[0,0,1] neg_hi:[0,0,1]
	v_pk_fma_f32 v[66:67], v[8:9], v[8:9], v[66:67] op_sel_hi:[1,0,1]
	v_pk_fma_f32 v[56:57], v[60:61], v[74:75], v[56:57] op_sel_hi:[0,1,1] neg_lo:[0,0,1] neg_hi:[0,0,1]
	v_pk_fma_f32 v[58:59], v[60:61], v[80:81], v[58:59] op_sel_hi:[0,1,1]
	v_pk_fma_f32 v[60:61], v[60:61], v[76:77], v[62:63] op_sel_hi:[0,1,1]
	v_xor_b32_e32 v63, 0x80000000, v77
	v_xor_b32_e32 v62, 0x80000000, v76
	v_pk_fma_f32 v[64:65], v[74:75], 0, v[76:77] op_sel_hi:[1,0,1]
	v_pk_mov_b32 v[76:77], v[66:67], v[68:69] op_sel:[1,0]
	v_pk_fma_f32 v[62:63], v[62:63], 0, v[74:75] op_sel_hi:[1,0,1]
	v_mov_b32_e32 v74, v68
	v_mov_b32_e32 v75, v67
	v_pk_mul_f32 v[66:67], v[66:67], v[76:77] op_sel:[1,0]
	v_cvt_pk_bf16_f32 v0, v54, s0
	v_pk_fma_f32 v[76:77], v[68:69], v[74:75], v[66:67] op_sel_hi:[0,1,1] neg_lo:[0,0,1] neg_hi:[0,0,1]
	v_pk_fma_f32 v[66:67], v[68:69], v[74:75], v[66:67] op_sel_hi:[0,1,1]
	v_perm_b32 v54, v4, v0, s41
	v_cvt_pk_bf16_f32 v0, v56, s0
	v_cvt_pk_bf16_f32 v4, v57, s0
	v_pk_mov_b32 v[74:75], v[66:67], v[76:77] op_sel:[1,0]
	v_perm_b32 v56, v4, v0, s41
	v_cvt_pk_bf16_f32 v0, v60, s0
	v_cvt_pk_bf16_f32 v4, v61, s0
	v_xor_b32_e32 v61, 0x80000000, v81
	v_xor_b32_e32 v60, 0x80000000, v80
	v_mov_b32_e32 v68, v76
	v_mov_b32_e32 v69, v67
	v_pk_mul_f32 v[74:75], v[66:67], v[74:75] op_sel:[1,0]
	v_perm_b32 v57, v23, v20, s41
	v_cvt_pk_bf16_f32 v20, v58, s0
	v_perm_b32 v58, v4, v0, s41
	v_pk_fma_f32 v[60:61], v[60:61], 0, v[78:79] op_sel_hi:[1,0,1]
	v_cvt_pk_bf16_f32 v0, v62, s0
	v_cvt_pk_bf16_f32 v4, v63, s0
	v_pk_fma_f32 v[62:63], v[78:79], 0, v[80:81] op_sel_hi:[1,0,1]
	v_pk_fma_f32 v[78:79], v[76:77], v[68:69], v[74:75] op_sel_hi:[0,1,1] neg_lo:[0,0,1] neg_hi:[0,0,1]
	v_pk_fma_f32 v[74:75], v[76:77], v[68:69], v[74:75] op_sel_hi:[0,1,1]
	v_mov_b32_e32 v79, v75
	v_pk_mul_f32 v[80:81], v[78:79], v[78:79]
	v_pk_mul_f32 v[82:83], v[74:75], v[78:79] op_sel:[1,0] op_sel_hi:[0,1]
	v_mov_b32_e32 v84, v80
	v_mov_b32_e32 v85, v82
	v_pk_mov_b32 v[80:81], v[80:81], v[82:83] op_sel:[1,0]
	v_cvt_pk_bf16_f32 v23, v59, s0
	v_pk_add_f32 v[82:83], v[84:85], v[80:81] neg_lo:[0,1] neg_hi:[0,1]
	v_pk_add_f32 v[80:81], v[84:85], v[80:81]
	v_mov_b32_e32 v84, v82
	v_mov_b32_e32 v85, v81
	v_pk_mul_f32 v[92:93], v[84:85], v[84:85]
	v_pk_mul_f32 v[94:95], v[80:81], v[84:85] op_sel:[1,0] op_sel_hi:[0,1]
	v_mov_b32_e32 v96, v92
	v_mov_b32_e32 v97, v94
	v_pk_mov_b32 v[92:93], v[92:93], v[94:95] op_sel:[1,0]
	v_perm_b32 v59, v23, v20, s41
	v_cvt_pk_bf16_f32 v20, v60, s0
	v_cvt_pk_bf16_f32 v23, v61, s0
	v_perm_b32 v60, v4, v0, s41
	v_cvt_pk_bf16_f32 v0, v64, s0
	v_cvt_pk_bf16_f32 v4, v65, s0
	v_pk_add_f32 v[94:95], v[96:97], v[92:93] neg_lo:[0,1] neg_hi:[0,1]
	v_pk_add_f32 v[92:93], v[96:97], v[92:93]
	v_perm_b32 v61, v23, v20, s41
	v_cvt_pk_bf16_f32 v20, v62, s0
	v_perm_b32 v62, v4, v0, s41
	v_mov_b32_e32 v96, v94
	v_mov_b32_e32 v97, v93
	v_mul_f32_e32 v0, v81, v93
	v_pk_mov_b32 v[86:87], v[80:81], v[82:83] op_sel:[1,0]
	v_pk_fma_f32 v[84:85], v[84:85], v[96:97], v[0:1] op_sel_hi:[1,1,0] neg_lo:[0,0,1] neg_hi:[0,0,1]
	v_mul_f32_e32 v0, v82, v93
	v_pk_fma_f32 v[86:87], v[86:87], v[96:97], v[0:1] op_sel_hi:[1,1,0]
	v_mul_f32_e32 v0, v67, v78
	v_pk_mul_f32 v[68:69], v[68:69], v[78:79]
	v_and_b32_e32 v103, 0xffff0000, v71
	v_lshlrev_b32_e32 v102, 16, v71
	v_fmac_f32_e32 v0, v76, v75
	v_sub_f32_e32 v4, v68, v69
	v_and_b32_e32 v97, 0xffff0000, v72
	v_lshlrev_b32_e32 v96, 16, v72
	v_and_b32_e32 v99, 0xffff0000, v70
	v_lshlrev_b32_e32 v98, 16, v70
	v_and_b32_e32 v101, 0xffff0000, v73
	v_lshlrev_b32_e32 v100, 16, v73
	v_pk_mul_f32 v[72:73], v[86:87], v[102:103] op_sel_hi:[0,1]
	v_cvt_pk_bf16_f32 v23, v63, s0
	v_cndmask_b32_e32 v4, v4, v78, vcc
	v_cndmask_b32_e32 v0, v0, v75, vcc
	v_pk_mul_f32 v[70:71], v[86:87], v[98:99] op_sel_hi:[0,1]
	v_pk_fma_f32 v[72:73], v[84:85], v[100:101], v[72:73] op_sel_hi:[0,1,1] neg_lo:[0,0,1] neg_hi:[0,0,1]
	v_pk_mul_f32 v[74:75], v[86:87], v[100:101] op_sel_hi:[0,1]
	v_perm_b32 v63, v23, v20, s41
	v_mov_b32_e32 v64, v8
	v_mov_b32_e32 v65, v8
	v_cndmask_b32_e64 v4, v4, v76, s[2:3]
	v_cndmask_b32_e64 v0, v0, v67, s[2:3]
	v_pk_fma_f32 v[70:71], v[84:85], v[96:97], v[70:71] op_sel_hi:[0,1,1] neg_lo:[0,0,1] neg_hi:[0,0,1]
	v_cvt_pk_bf16_f32 v8, v72, s0
	v_cvt_pk_bf16_f32 v20, v73, s0
	v_pk_mul_f32 v[72:73], v[86:87], v[96:97] op_sel_hi:[0,1]
	v_pk_fma_f32 v[74:75], v[84:85], v[102:103], v[74:75] op_sel_hi:[0,1,1]
	v_pk_mul_f32 v[76:77], v[92:93], v[102:103] op_sel:[1,0]
	v_cndmask_b32_e64 v66, v4, 1.0, s[4:5]
	v_cndmask_b32_e64 v69, v0, 0, s[4:5]
	v_cvt_pk_bf16_f32 v0, v70, s0
	v_cvt_pk_bf16_f32 v4, v71, s0
	v_perm_b32 v71, v20, v8, s41
	v_pk_fma_f32 v[72:73], v[84:85], v[98:99], v[72:73] op_sel_hi:[0,1,1]
	v_cvt_pk_bf16_f32 v8, v74, s0
	v_cvt_pk_bf16_f32 v20, v75, s0
	v_pk_mul_f32 v[74:75], v[92:93], v[98:99] op_sel:[1,0]
	v_pk_fma_f32 v[76:77], v[94:95], v[100:101], v[76:77] op_sel_hi:[0,1,1] neg_lo:[0,0,1] neg_hi:[0,0,1]
	v_pk_mul_f32 v[78:79], v[92:93], v[100:101] op_sel:[1,0]
	v_perm_b32 v70, v4, v0, s41
	v_cvt_pk_bf16_f32 v0, v72, s0
	v_cvt_pk_bf16_f32 v4, v73, s0
	v_perm_b32 v73, v20, v8, s41
	v_pk_fma_f32 v[74:75], v[94:95], v[96:97], v[74:75] op_sel_hi:[0,1,1] neg_lo:[0,0,1] neg_hi:[0,0,1]
	v_cvt_pk_bf16_f32 v8, v76, s0
	v_cvt_pk_bf16_f32 v20, v77, s0
	v_pk_mul_f32 v[76:77], v[92:93], v[96:97] op_sel:[1,0]
	v_pk_fma_f32 v[78:79], v[94:95], v[102:103], v[78:79] op_sel_hi:[0,1,1]
	v_pk_mul_f32 v[84:85], v[80:81], v[102:103] op_sel:[1,0]
	v_perm_b32 v72, v4, v0, s41
	v_cvt_pk_bf16_f32 v0, v74, s0
	v_cvt_pk_bf16_f32 v4, v75, s0
	v_perm_b32 v75, v20, v8, s41
	v_pk_fma_f32 v[76:77], v[94:95], v[98:99], v[76:77] op_sel_hi:[0,1,1]
	v_cvt_pk_bf16_f32 v8, v78, s0
	v_cvt_pk_bf16_f32 v20, v79, s0
	v_pk_fma_f32 v[84:85], v[82:83], v[100:101], v[84:85] op_sel_hi:[0,1,1] neg_lo:[0,0,1] neg_hi:[0,0,1]
	s_waitcnt vmcnt(4)
; template <int DIR>
; __device__ __forceinline__ void s5_local_dir(const bf16_t* UZ, unsigned char* ws, int gw, int NGW, int lane) {
;     ...
;     for (int t = 0; t < 4; ++t) {
;         const int p = 16 * t + fr;
;         const bf16x4 b_re = *(const bf16x4*)(Bb + (2 * p) * 16 + 4 * fq), b_im = *(const bf16x4*)(Bb + (2 * p + 1) * 16 + 4 * fq);
;         const f32x4 ap = ((const f32x4*)(ws + WS_APOW))[pair * 64 + p];
;         const float ar = ap.x, ai = ap.y;
;         float r2 = ar, i2 = ai; cmul(r2, i2, ar, ai);
;         float r4 = r2, i4 = i2; cmul(r4, i4, r2, i2);
;         float r8 = r4, i8 = i4; cmul(r8, i8, r4, i4);
;         float r12 = r8, i12 = i8; cmul(r12, i12, r4, i4);
;         float r16 = r8, i16 = i8; cmul(r16, i16, r8, i8);
;         float r32 = r16, i32 = i16; cmul(r32, i32, r16, i16);
;         float r48 = r32, i48 = i32; cmul(r48, i48, r16, i16);
;         a1r[t] = ar; a1i[t] = ai; a64r[t] = ap.z; a64i[t] = ap.w;
;         const int e = DIR ? fq : 3 - fq;
;         wr_[t] = e == 0 ? 1.f : e == 1 ? r4 : e == 2 ? r8 : r12; wi_[t] = e == 0 ? 0.f : e == 1 ? i4 : e == 2 ? i8 : i12;
; #pragma unroll
;         for (int m = 0; m < 4; ++m) {
;             const int em = DIR ? m : 3 - m;
;             const float pr = em == 0 ? 1.f : em == 1 ? r16 : em == 2 ? r32 : r48, pi = em == 0 ? 0.f : em == 1 ? i16 : em == 2 ? i32 : i48;
;             Bre[m][t] = cscale_bf(b_re, b_im, pr, pi, false); Bim[m][t] = cscale_bf(b_re, b_im, pr, pi, true);
;         }
	v_pk_mul_f32 v[92:93], v[12:13], v[12:13] op_sel:[1,1] op_sel_hi:[1,0]
	v_perm_b32 v74, v4, v0, s41
	v_cvt_pk_bf16_f32 v4, v77, s0
	v_perm_b32 v77, v20, v8, s41
	v_pk_mul_f32 v[78:79], v[80:81], v[98:99] op_sel:[1,0]
	v_cvt_pk_bf16_f32 v8, v84, s0
	v_cvt_pk_bf16_f32 v20, v85, s0
	v_pk_mul_f32 v[84:85], v[80:81], v[96:97] op_sel:[1,0]
	v_pk_mul_f32 v[80:81], v[80:81], v[100:101] op_sel:[1,0]
	v_pk_fma_f32 v[94:95], v[12:13], v[12:13], v[92:93] op_sel_hi:[1,0,1] neg_lo:[0,0,1] neg_hi:[0,0,1]
	v_pk_fma_f32 v[92:93], v[12:13], v[12:13], v[92:93] op_sel_hi:[1,0,1]
	v_pk_fma_f32 v[78:79], v[82:83], v[96:97], v[78:79] op_sel_hi:[0,1,1] neg_lo:[0,0,1] neg_hi:[0,0,1]
	v_pk_fma_f32 v[80:81], v[82:83], v[102:103], v[80:81] op_sel_hi:[0,1,1]
	v_pk_fma_f32 v[82:83], v[82:83], v[98:99], v[84:85] op_sel_hi:[0,1,1]
	v_xor_b32_e32 v85, 0x80000000, v99
	v_xor_b32_e32 v84, 0x80000000, v98
	v_pk_fma_f32 v[86:87], v[96:97], 0, v[98:99] op_sel_hi:[1,0,1]
	v_pk_mov_b32 v[98:99], v[92:93], v[94:95] op_sel:[1,0]
	v_pk_fma_f32 v[84:85], v[84:85], 0, v[96:97] op_sel_hi:[1,0,1]
	v_mov_b32_e32 v96, v94
	v_mov_b32_e32 v97, v93
	v_pk_mul_f32 v[92:93], v[92:93], v[98:99] op_sel:[1,0]
	v_cvt_pk_bf16_f32 v0, v76, s0
	v_pk_fma_f32 v[98:99], v[94:95], v[96:97], v[92:93] op_sel_hi:[0,1,1] neg_lo:[0,0,1] neg_hi:[0,0,1]
	v_pk_fma_f32 v[92:93], v[94:95], v[96:97], v[92:93] op_sel_hi:[0,1,1]
	v_perm_b32 v76, v4, v0, s41
	v_cvt_pk_bf16_f32 v0, v78, s0
	v_cvt_pk_bf16_f32 v4, v79, s0
	v_pk_mov_b32 v[96:97], v[92:93], v[98:99] op_sel:[1,0]
	v_perm_b32 v78, v4, v0, s41
	v_cvt_pk_bf16_f32 v0, v82, s0
	v_cvt_pk_bf16_f32 v4, v83, s0
	v_xor_b32_e32 v83, 0x80000000, v103
	v_xor_b32_e32 v82, 0x80000000, v102
	v_mov_b32_e32 v94, v98
	v_mov_b32_e32 v95, v93
	v_pk_mul_f32 v[96:97], v[92:93], v[96:97] op_sel:[1,0]
	v_perm_b32 v79, v20, v8, s41
	v_cvt_pk_bf16_f32 v8, v80, s0
	v_perm_b32 v80, v4, v0, s41
	v_pk_fma_f32 v[82:83], v[82:83], 0, v[100:101] op_sel_hi:[1,0,1]
	v_cvt_pk_bf16_f32 v0, v84, s0
	v_cvt_pk_bf16_f32 v4, v85, s0
	v_pk_fma_f32 v[84:85], v[100:101], 0, v[102:103] op_sel_hi:[1,0,1]
	v_pk_fma_f32 v[100:101], v[98:99], v[94:95], v[96:97] op_sel_hi:[0,1,1] neg_lo:[0,0,1] neg_hi:[0,0,1]
	v_pk_fma_f32 v[96:97], v[98:99], v[94:95], v[96:97] op_sel_hi:[0,1,1]
	v_mov_b32_e32 v101, v97
	v_pk_mul_f32 v[102:103], v[100:101], v[100:101]
	v_pk_mul_f32 v[104:105], v[96:97], v[100:101] op_sel:[1,0] op_sel_hi:[0,1]
	v_mov_b32_e32 v106, v102
	v_mov_b32_e32 v107, v104
	v_pk_mov_b32 v[102:103], v[102:103], v[104:105] op_sel:[1,0]
	v_cvt_pk_bf16_f32 v20, v81, s0
	v_pk_add_f32 v[104:105], v[106:107], v[102:103] neg_lo:[0,1] neg_hi:[0,1]
	v_pk_add_f32 v[102:103], v[106:107], v[102:103]
	v_mov_b32_e32 v106, v104
	v_mov_b32_e32 v107, v103
	v_pk_mul_f32 v[110:111], v[106:107], v[106:107]
	v_pk_mul_f32 v[112:113], v[102:103], v[106:107] op_sel:[1,0] op_sel_hi:[0,1]
	v_mov_b32_e32 v114, v110
	v_mov_b32_e32 v115, v112
	v_pk_mov_b32 v[110:111], v[110:111], v[112:113] op_sel:[1,0]
	v_perm_b32 v81, v20, v8, s41
	v_cvt_pk_bf16_f32 v8, v82, s0
	v_cvt_pk_bf16_f32 v20, v83, s0
	v_perm_b32 v82, v4, v0, s41
	v_cvt_pk_bf16_f32 v0, v86, s0
	v_cvt_pk_bf16_f32 v4, v87, s0
	v_pk_add_f32 v[112:113], v[114:115], v[110:111] neg_lo:[0,1] neg_hi:[0,1]
	v_pk_add_f32 v[110:111], v[114:115], v[110:111]
	v_perm_b32 v83, v20, v8, s41
	v_cvt_pk_bf16_f32 v8, v84, s0
	v_perm_b32 v84, v4, v0, s41
	v_mov_b32_e32 v114, v112
	v_mov_b32_e32 v115, v111
	v_mul_f32_e32 v0, v103, v111
	v_pk_mov_b32 v[108:109], v[102:103], v[104:105] op_sel:[1,0]
	v_pk_fma_f32 v[106:107], v[106:107], v[114:115], v[0:1] op_sel_hi:[1,1,0] neg_lo:[0,0,1] neg_hi:[0,0,1]
	v_mul_f32_e32 v0, v104, v111
	v_pk_fma_f32 v[108:109], v[108:109], v[114:115], v[0:1] op_sel_hi:[1,1,0]
	v_mul_f32_e32 v0, v93, v100
	v_pk_mul_f32 v[94:95], v[94:95], v[100:101]
	v_and_b32_e32 v123, 0xffff0000, v91
	v_lshlrev_b32_e32 v122, 16, v91
	v_fmac_f32_e32 v0, v98, v97
	v_sub_f32_e32 v4, v94, v95
	v_and_b32_e32 v119, 0xffff0000, v90
	v_lshlrev_b32_e32 v118, 16, v90
	v_and_b32_e32 v121, 0xffff0000, v89
	v_lshlrev_b32_e32 v120, 16, v89
	v_pk_mul_f32 v[90:91], v[108:109], v[122:123] op_sel_hi:[0,1]
	v_cvt_pk_bf16_f32 v20, v85, s0
	v_cndmask_b32_e32 v4, v4, v100, vcc
	v_cndmask_b32_e32 v0, v0, v97, vcc
	v_and_b32_e32 v117, 0xffff0000, v88
	v_lshlrev_b32_e32 v116, 16, v88
	v_pk_mul_f32 v[88:89], v[108:109], v[118:119] op_sel_hi:[0,1]
	v_pk_fma_f32 v[90:91], v[106:107], v[120:121], v[90:91] op_sel_hi:[0,1,1] neg_lo:[0,0,1] neg_hi:[0,0,1]
	v_pk_mul_f32 v[96:97], v[108:109], v[120:121] op_sel_hi:[0,1]
	v_perm_b32 v85, v20, v8, s41
	v_mov_b32_e32 v86, v12
	v_mov_b32_e32 v87, v12
	v_cndmask_b32_e64 v4, v4, v98, s[2:3]
	v_cndmask_b32_e64 v0, v0, v93, s[2:3]
	v_pk_fma_f32 v[88:89], v[106:107], v[116:117], v[88:89] op_sel_hi:[0,1,1] neg_lo:[0,0,1] neg_hi:[0,0,1]
	v_cvt_pk_bf16_f32 v8, v90, s0
	v_cvt_pk_bf16_f32 v12, v91, s0
	v_pk_mul_f32 v[90:91], v[108:109], v[116:117] op_sel_hi:[0,1]
	v_pk_fma_f32 v[96:97], v[106:107], v[122:123], v[96:97] op_sel_hi:[0,1,1]
	v_pk_mul_f32 v[98:99], v[110:111], v[122:123] op_sel:[1,0]
	v_cndmask_b32_e64 v92, v4, 1.0, s[4:5]
	v_cndmask_b32_e64 v95, v0, 0, s[4:5]
	v_cvt_pk_bf16_f32 v0, v88, s0
	v_cvt_pk_bf16_f32 v4, v89, s0
	v_perm_b32 v89, v12, v8, s41
	v_pk_fma_f32 v[90:91], v[106:107], v[118:119], v[90:91] op_sel_hi:[0,1,1]
	v_cvt_pk_bf16_f32 v8, v96, s0
	v_cvt_pk_bf16_f32 v12, v97, s0
	v_pk_mul_f32 v[96:97], v[110:111], v[118:119] op_sel:[1,0]
; template <int DIR>
; __device__ __forceinline__ void s5_local_dir(const bf16_t* UZ, unsigned char* ws, int gw, int NGW, int lane) {
;     ...
;         const int e = DIR ? fq : 3 - fq;
;         wr_[t] = e == 0 ? 1.f : e == 1 ? r4 : e == 2 ? r8 : r12; wi_[t] = e == 0 ? 0.f : e == 1 ? i4 : e == 2 ? i8 : i12;
; #pragma unroll
;         for (int m = 0; m < 4; ++m) {
;             const int em = DIR ? m : 3 - m;
;             const float pr = em == 0 ? 1.f : em == 1 ? r16 : em == 2 ? r32 : r48, pi = em == 0 ? 0.f : em == 1 ? i16 : em == 2 ? i32 : i48;
;             Bre[m][t] = cscale_bf(b_re, b_im, pr, pi, false); Bim[m][t] = cscale_bf(b_re, b_im, pr, pi, true);
;         }
;     }
;     const int qd = gw >> 7, b = qd >> 2, q = qd & 3;
;     if (qd >= 16) return;
;     const int c0 = 17 * q, c1 = q < 3 ? c0 + 17 : 67;
;     float Rr[4] = {0.f, 0.f, 0.f, 0.f}, Ri[4] = {0.f, 0.f, 0.f, 0.f};
;     float* ebase = E + ((size_t)((b * 2 + DIR) * 64 + g) * NCHUNK) * 128;
;     bf16x4 Un[4];
;     load_uf(Un, UZ, chunk_rowbase(b, DIR, c0), g, lane);
;     for (int c = c0; c < c1; ++c) {
;         bf16x4 Uf[4];
; #pragma unroll
;         for (int m = 0; m < 4; ++m) Uf[m] = Un[m];
;         if (c + 1 < c1) load_uf(Un, UZ, chunk_rowbase(b, DIR, c + 1), g, lane);
;         float* e = ebase + (size_t)c * 128;
	v_pk_fma_f32 v[98:99], v[112:113], v[120:121], v[98:99] op_sel_hi:[0,1,1] neg_lo:[0,0,1] neg_hi:[0,0,1]
	v_pk_mul_f32 v[100:101], v[110:111], v[120:121] op_sel:[1,0]
	v_perm_b32 v88, v4, v0, s41
	v_cvt_pk_bf16_f32 v0, v90, s0
	v_cvt_pk_bf16_f32 v4, v91, s0
	v_perm_b32 v91, v12, v8, s41
	v_pk_fma_f32 v[96:97], v[112:113], v[116:117], v[96:97] op_sel_hi:[0,1,1] neg_lo:[0,0,1] neg_hi:[0,0,1]
	v_cvt_pk_bf16_f32 v8, v98, s0
	v_cvt_pk_bf16_f32 v12, v99, s0
	v_pk_mul_f32 v[98:99], v[110:111], v[116:117] op_sel:[1,0]
	v_pk_fma_f32 v[100:101], v[112:113], v[122:123], v[100:101] op_sel_hi:[0,1,1]
	v_pk_mul_f32 v[106:107], v[102:103], v[122:123] op_sel:[1,0]
	v_perm_b32 v90, v4, v0, s41
	v_cvt_pk_bf16_f32 v0, v96, s0
	v_cvt_pk_bf16_f32 v4, v97, s0
	v_perm_b32 v97, v12, v8, s41
	v_pk_fma_f32 v[98:99], v[112:113], v[118:119], v[98:99] op_sel_hi:[0,1,1]
	v_cvt_pk_bf16_f32 v8, v100, s0
	v_cvt_pk_bf16_f32 v12, v101, s0
	v_pk_fma_f32 v[106:107], v[104:105], v[120:121], v[106:107] op_sel_hi:[0,1,1] neg_lo:[0,0,1] neg_hi:[0,0,1]
	v_perm_b32 v96, v4, v0, s41
	v_cvt_pk_bf16_f32 v4, v99, s0
	v_perm_b32 v99, v12, v8, s41
	v_pk_mul_f32 v[100:101], v[102:103], v[118:119] op_sel:[1,0]
	v_cvt_pk_bf16_f32 v8, v106, s0
	v_cvt_pk_bf16_f32 v12, v107, s0
	v_pk_mul_f32 v[106:107], v[102:103], v[116:117] op_sel:[1,0]
	v_pk_mul_f32 v[102:103], v[102:103], v[120:121] op_sel:[1,0]
	v_pk_fma_f32 v[100:101], v[104:105], v[116:117], v[100:101] op_sel_hi:[0,1,1] neg_lo:[0,0,1] neg_hi:[0,0,1]
	v_pk_fma_f32 v[102:103], v[104:105], v[122:123], v[102:103] op_sel_hi:[0,1,1]
	v_pk_fma_f32 v[104:105], v[104:105], v[118:119], v[106:107] op_sel_hi:[0,1,1]
	v_add_u32_e32 v106, s25, v127
	v_ashrrev_i32_e32 v107, 31, v106
	v_lshlrev_b64 v[106:107], 12, v[106:107]
	v_lshl_add_u64 v[106:107], v[16:17], 0, v[106:107]
	s_mov_b32 s2, 0x10000
	v_add_co_u32_e32 v124, vcc, s2, v106
	s_mov_b32 s2, 0x20000
	s_nop 0
	v_addc_co_u32_e32 v125, vcc, 0, v107, vcc
	v_add_co_u32_e32 v128, vcc, s2, v106
	s_mov_b32 s2, 0x30000
	s_nop 0
	v_addc_co_u32_e32 v129, vcc, 0, v107, vcc
	v_add_co_u32_e32 v130, vcc, s2, v106
	v_cvt_pk_bf16_f32 v0, v98, s0
	s_nop 0
	v_addc_co_u32_e32 v131, vcc, 0, v107, vcc
	s_waitcnt vmcnt(0)
	v_mov_b64_e32 v[108:109], v[152:153]
	v_mov_b64_e32 v[112:113], v[154:155]
	v_mov_b64_e32 v[114:115], v[156:157]
	v_mov_b64_e32 v[110:111], v[158:159]
	v_perm_b32 v98, v4, v0, s41
	v_cvt_pk_bf16_f32 v0, v100, s0
	v_cvt_pk_bf16_f32 v4, v101, s0
	v_xor_b32_e32 v107, 0x80000000, v119
	v_xor_b32_e32 v106, 0x80000000, v118
	v_perm_b32 v100, v4, v0, s41
	v_cvt_pk_bf16_f32 v0, v104, s0
	v_cvt_pk_bf16_f32 v4, v105, s0
	v_xor_b32_e32 v105, 0x80000000, v123
	v_xor_b32_e32 v104, 0x80000000, v122
	v_pk_fma_f32 v[106:107], v[106:107], 0, v[116:117] op_sel_hi:[1,0,1]
	v_perm_b32 v101, v12, v8, s41
	v_cvt_pk_bf16_f32 v8, v102, s0
	v_cvt_pk_bf16_f32 v12, v103, s0
	v_perm_b32 v102, v4, v0, s41
	v_pk_fma_f32 v[104:105], v[104:105], 0, v[120:121] op_sel_hi:[1,0,1]
	v_cvt_pk_bf16_f32 v0, v106, s0
	v_cvt_pk_bf16_f32 v4, v107, s0
	v_pk_fma_f32 v[116:117], v[116:117], 0, v[118:119] op_sel_hi:[1,0,1]
	v_perm_b32 v103, v12, v8, s41
	v_cvt_pk_bf16_f32 v8, v104, s0
	v_cvt_pk_bf16_f32 v12, v105, s0
	v_perm_b32 v104, v4, v0, s41
	v_pk_fma_f32 v[106:107], v[120:121], 0, v[122:123] op_sel_hi:[1,0,1]
	v_cvt_pk_bf16_f32 v0, v116, s0
	v_cvt_pk_bf16_f32 v4, v117, s0
	v_perm_b32 v105, v12, v8, s41
	v_cvt_pk_bf16_f32 v8, v106, s0
	v_perm_b32 v106, v4, v0, s41
	v_mbcnt_lo_u32_b32 v0, -1, 0
	v_cvt_pk_bf16_f32 v12, v107, s0
	v_mbcnt_hi_u32_b32 v0, -1, v0
	v_perm_b32 v107, v12, v8, s41
	s_lshl_b32 s41, s23, 12
	s_lshl_b32 s42, s23, 8
	v_and_b32_e32 v8, 64, v0
	s_add_i32 s4, s38, s36
	s_bfe_u32 s23, s40, 0x20007
	s_addk_i32 s41, 0xff00
	s_addk_i32 s42, 0x4000
	v_xor_b32_e32 v4, 16, v0
	v_add_u32_e32 v8, 64, v8
	s_mul_hi_i32 s5, s4, 0x8800
	s_mul_i32 s4, s4, 0x8800
	s_mulk_i32 s23, 0x2200
	v_cmp_lt_i32_e32 vcc, v4, v8
	s_add_u32 s4, s4, s23
	s_addc_u32 s5, s5, 0
	v_cndmask_b32_e32 v4, v0, v4, vcc
	v_lshlrev_b32_e32 v128, 2, v4
	v_xor_b32_e32 v4, 32, v0
	s_add_u32 s4, s30, s4
	v_cmp_lt_i32_e32 vcc, v4, v8
	v_lshlrev_b32_e32 v20, 2, v126
	s_addc_u32 s5, s31, s5
	v_cndmask_b32_e32 v0, v0, v4, vcc
	v_lshl_add_u64 v[116:117], s[4:5], 0, v[20:21]
	s_mov_b64 s[4:5], 0x1700100
	v_or_b32_e32 v20, s22, v127
	v_lshlrev_b32_e32 v129, 2, v0
	v_cmp_gt_u32_e64 s[2:3], 16, v126
	v_xor_b32_e32 v0, 0x80000000, v1
	v_mov_b32_e32 v23, v22
	v_xor_b32_e32 v24, 0x80000000, v25
	v_xor_b32_e32 v4, 0x80000000, v5
	v_mov_b32_e32 v45, v44
	v_xor_b32_e32 v46, 0x80000000, v47
	v_xor_b32_e32 v8, 0x80000000, v9
	v_mov_b32_e32 v67, v66
	v_xor_b32_e32 v68, 0x80000000, v69
	v_xor_b32_e32 v12, 0x80000000, v13
	v_mov_b32_e32 v93, v92
	v_xor_b32_e32 v94, 0x80000000, v95
	v_lshl_add_u64 v[116:117], v[116:117], 0, s[4:5]
	v_add_u32_e32 v20, 0x70, v20
	s_mov_b64 s[4:5], 0x200
	v_mov_b32_e32 v133, v21
	v_mov_b32_e32 v131, v21
	v_mov_b32_e32 v127, v21
	v_mov_b32_e32 v135, v21
	v_mov_b32_e32 v134, v21
	v_mov_b32_e32 v132, v21
	v_mov_b32_e32 v130, v21
	v_and_b32_e32 v244, 16, v126
	v_and_b32_e32 v245, 32, v126
	v_cmp_ne_u32_e64 s[96:97], 0, v244
	v_cmp_ne_u32_e32 vcc, 0, v245
	s_nop 1
	v_cndmask_b32_e32 v244, v2, v10, vcc
	v_cndmask_b32_e32 v245, v6, v14, vcc
	v_cndmask_b32_e64 v242, v244, v245, s[96:97]
	v_cndmask_b32_e32 v244, v3, v11, vcc
	v_cndmask_b32_e32 v245, v7, v15, vcc
	v_cndmask_b32_e64 v243, v244, v245, s[96:97]
